# merge-phase GEMM loops: next K-tile global loads reissued right after each LDS staging write (continuous prefetch), on top of split-step gemm4 loops
# speedup vs baseline: 1.0343x; 1.0095x over previous
.LBB0_23:
	s_cmpk_gt_u32 s45, 0xfbf
	s_cselect_b64 s[28:29], -1, 0
	s_cmp_lg_u32 s45, 0
	s_cbranch_scc1 .Ls_nosetup_ff2
	v_add_u32_e32 v176, v182, v180
	v_add_u32_e32 v243, v182, v183
	v_add_u32_e32 v241, v181, v180
	v_add_u32_e32 v242, v181, v183
	v_or_b32_e32 v182, 0x4000, v214
	v_lshrrev_b32_e32 v180, 3, v184
	v_and_b32_e32 v181, 7, v184
	v_lshlrev_b32_e32 v180, 13, v180
	v_lshl_add_u32 v180, v181, 4, v180
	s_cmp_eq_u32 s100, 0
	s_cbranch_scc1 .Ls_nosetup_ff2
	s_mov_b32 s100, 0
	s_waitcnt vmcnt(0)
	ds_write_b128 v214, v[0:3]
	ds_write_b128 v214, v[4:7] offset:4096
	ds_write_b128 v214, v[16:19] offset:16384
	ds_write_b128 v214, v[20:23] offset:20480
	ds_write_b128 v214, v[32:35] offset:32768
	ds_write_b128 v214, v[36:39] offset:36864
	ds_write_b128 v214, v[40:43] offset:40960
	ds_write_b128 v214, v[44:47] offset:45056
	s_movk_i32 s101, 0x80
	s_add_u32 s86, s50, s101
	s_addc_u32 s87, s51, 0
	s_add_u32 s34, s92, s101
	s_addc_u32 s35, s93, 0
	global_load_dwordx4 v[32:35], v180, s[34:35]
	s_add_u32 s98, s34, 0x40000
	s_addc_u32 s99, s35, 0
	global_load_dwordx4 v[36:39], v180, s[98:99]
	global_load_dwordx4 v[0:3], v180, s[86:87]
	s_add_u32 s98, s86, 0x40000
	s_addc_u32 s99, s87, 0
	global_load_dwordx4 v[4:7], v180, s[98:99]
	s_add_u32 s98, s86, 0x100000
	s_addc_u32 s99, s87, 0
	global_load_dwordx4 v[16:19], v180, s[98:99]
	s_add_u32 s98, s86, 0x140000
	s_addc_u32 s99, s87, 0
	global_load_dwordx4 v[20:23], v180, s[98:99]
	s_add_u32 s98, s34, 0x80000
	s_addc_u32 s99, s35, 0
	global_load_dwordx4 v[40:43], v180, s[98:99]
	s_add_u32 s98, s34, 0xc0000
	s_addc_u32 s99, s35, 0
	global_load_dwordx4 v[44:47], v180, s[98:99]
	s_waitcnt lgkmcnt(0)
	s_barrier
.Ls_nosetup_ff2:
	s_add_i32 s101, s45, 64
	s_cmpk_ge_u32 s101, 0x1000
	s_cselect_b32 s98, 0x1000, 0
	s_cselect_b32 s99, s94, 0
	s_sub_u32 s101, s101, s98
	s_lshl_b32 s101, s101, 1
	s_cmp_lg_u32 s99, 0
	s_cselect_b64 s[84:85], s[38:39], s[50:51]
	s_add_u32 s84, s84, s101
	s_addc_u32 s85, s85, 0
	s_add_i32 s101, s45, 128
	s_cmpk_ge_u32 s101, 0x1000
	s_cselect_b32 s98, 0x1000, 0
	s_cselect_b32 s99, s94, 0
	s_sub_u32 s101, s101, s98
	s_lshl_b32 s101, s101, 1
	s_cmp_lg_u32 s99, 0
	s_cselect_b64 s[86:87], s[38:39], s[50:51]
	s_cselect_b64 s[34:35], s[42:43], s[92:93]
	s_add_u32 s86, s86, s101
	s_addc_u32 s87, s87, 0
	s_add_u32 s34, s34, s101
	s_addc_u32 s35, s35, 0
	ds_read_b128 v[216:219], v176 offset:32768
	ds_read_b128 v[232:235], v241
	ds_read_b128 v[220:223], v176 offset:34816
	ds_read_b128 v[224:227], v176 offset:36864
	ds_read_b128 v[228:231], v176 offset:38912
	ds_read_b128 v[244:247], v241 offset:2048
	ds_read_b128 v[248:251], v241 offset:4096
	ds_read_b128 v[252:255], v241 offset:6144
	s_waitcnt lgkmcnt(6)
	v_mfma_f32_16x16x32_bf16 v[172:175], v[216:219], v[232:235], v[172:175]
	s_waitcnt lgkmcnt(5)
	v_mfma_f32_16x16x32_bf16 v[168:171], v[220:223], v[232:235], v[168:171]
	s_waitcnt lgkmcnt(4)
	v_mfma_f32_16x16x32_bf16 v[164:167], v[224:227], v[232:235], v[164:167]
	s_waitcnt lgkmcnt(3)
	v_mfma_f32_16x16x32_bf16 v[160:163], v[228:231], v[232:235], v[160:163]
	ds_read_b128 v[232:235], v242
	s_waitcnt vmcnt(11)
	ds_write_b128 v214, v[8:11] offset:8192
	s_add_u32 s98, s84, 0x80000
	s_addc_u32 s99, s85, 0
	global_load_dwordx4 v[8:11], v180, s[98:99]
	s_waitcnt lgkmcnt(4)
	v_mfma_f32_16x16x32_bf16 v[156:159], v[216:219], v[244:247], v[156:159]
	v_mfma_f32_16x16x32_bf16 v[152:155], v[220:223], v[244:247], v[152:155]
	v_mfma_f32_16x16x32_bf16 v[148:151], v[224:227], v[244:247], v[148:151]
	v_mfma_f32_16x16x32_bf16 v[144:147], v[228:231], v[244:247], v[144:147]
	ds_read_b128 v[244:247], v242 offset:2048
	s_waitcnt vmcnt(11)
	ds_write_b128 v214, v[12:15] offset:12288
	s_add_u32 s98, s84, 0xc0000
	s_addc_u32 s99, s85, 0
	global_load_dwordx4 v[12:15], v180, s[98:99]
	s_waitcnt lgkmcnt(5)
	v_mfma_f32_16x16x32_bf16 v[140:143], v[216:219], v[248:251], v[140:143]
	s_waitcnt lgkmcnt(4)
	v_mfma_f32_16x16x32_bf16 v[124:127], v[216:219], v[252:255], v[124:127]
	ds_read_b128 v[216:219], v243 offset:32768
	v_mfma_f32_16x16x32_bf16 v[136:139], v[220:223], v[248:251], v[136:139]
	v_mfma_f32_16x16x32_bf16 v[120:123], v[220:223], v[252:255], v[120:123]
	ds_read_b128 v[220:223], v243 offset:34816
	v_mfma_f32_16x16x32_bf16 v[132:135], v[224:227], v[248:251], v[132:135]
	v_mfma_f32_16x16x32_bf16 v[116:119], v[224:227], v[252:255], v[116:119]
	ds_read_b128 v[224:227], v243 offset:36864
	v_mfma_f32_16x16x32_bf16 v[128:131], v[228:231], v[248:251], v[128:131]
	v_mfma_f32_16x16x32_bf16 v[112:115], v[228:231], v[252:255], v[112:115]
	ds_read_b128 v[228:231], v243 offset:38912
	ds_read_b128 v[248:251], v242 offset:4096
	ds_read_b128 v[252:255], v242 offset:6144
	s_waitcnt vmcnt(11)
	ds_write_b128 v214, v[24:27] offset:24576
	s_add_u32 s98, s84, 0x180000
	s_addc_u32 s99, s85, 0
	global_load_dwordx4 v[24:27], v180, s[98:99]
	s_waitcnt lgkmcnt(6)
	v_mfma_f32_16x16x32_bf16 v[172:175], v[216:219], v[232:235], v[172:175]
	v_mfma_f32_16x16x32_bf16 v[156:159], v[216:219], v[244:247], v[156:159]
	s_waitcnt lgkmcnt(5)
	v_mfma_f32_16x16x32_bf16 v[168:171], v[220:223], v[232:235], v[168:171]
	v_mfma_f32_16x16x32_bf16 v[152:155], v[220:223], v[244:247], v[152:155]
	s_waitcnt vmcnt(11)
	ds_write_b128 v214, v[28:31] offset:28672
	s_add_u32 s98, s84, 0x1c0000
	s_addc_u32 s99, s85, 0
	global_load_dwordx4 v[28:31], v180, s[98:99]
	s_waitcnt lgkmcnt(5)
	v_mfma_f32_16x16x32_bf16 v[164:167], v[224:227], v[232:235], v[164:167]
	v_mfma_f32_16x16x32_bf16 v[148:151], v[224:227], v[244:247], v[148:151]
	s_waitcnt lgkmcnt(4)
	v_mfma_f32_16x16x32_bf16 v[160:163], v[228:231], v[232:235], v[160:163]
	v_mfma_f32_16x16x32_bf16 v[144:147], v[228:231], v[244:247], v[144:147]
	s_waitcnt vmcnt(11)
	ds_write_b128 v182, v[32:35] offset:32768
	global_load_dwordx4 v[32:35], v180, s[34:35]
	s_waitcnt lgkmcnt(4)
	v_mfma_f32_16x16x32_bf16 v[140:143], v[216:219], v[248:251], v[140:143]
	v_mfma_f32_16x16x32_bf16 v[136:139], v[220:223], v[248:251], v[136:139]
	v_mfma_f32_16x16x32_bf16 v[132:135], v[224:227], v[248:251], v[132:135]
	v_mfma_f32_16x16x32_bf16 v[128:131], v[228:231], v[248:251], v[128:131]
	s_waitcnt vmcnt(11)
	ds_write_b128 v182, v[36:39] offset:36864
	s_add_u32 s98, s34, 0x40000
	s_addc_u32 s99, s35, 0
	global_load_dwordx4 v[36:39], v180, s[98:99]
	s_waitcnt lgkmcnt(0)
	s_barrier
	v_mfma_f32_16x16x32_bf16 v[124:127], v[216:219], v[252:255], v[124:127]
	v_mfma_f32_16x16x32_bf16 v[120:123], v[220:223], v[252:255], v[120:123]
	v_mfma_f32_16x16x32_bf16 v[116:119], v[224:227], v[252:255], v[116:119]
	v_mfma_f32_16x16x32_bf16 v[112:115], v[228:231], v[252:255], v[112:115]
	ds_read_b128 v[216:219], v176 offset:32768
	ds_read_b128 v[232:235], v241 offset:8192
	ds_read_b128 v[220:223], v176 offset:34816
	ds_read_b128 v[224:227], v176 offset:36864
	ds_read_b128 v[228:231], v176 offset:38912
	ds_read_b128 v[244:247], v241 offset:10240
	ds_read_b128 v[248:251], v241 offset:12288
	ds_read_b128 v[252:255], v241 offset:14336
	s_waitcnt lgkmcnt(6)
	v_mfma_f32_16x16x32_bf16 v[108:111], v[216:219], v[232:235], v[108:111]
	s_waitcnt lgkmcnt(5)
	v_mfma_f32_16x16x32_bf16 v[104:107], v[220:223], v[232:235], v[104:107]
	s_waitcnt lgkmcnt(4)
	v_mfma_f32_16x16x32_bf16 v[100:103], v[224:227], v[232:235], v[100:103]
	s_waitcnt lgkmcnt(3)
	v_mfma_f32_16x16x32_bf16 v[96:99], v[228:231], v[232:235], v[96:99]
	ds_read_b128 v[232:235], v242 offset:8192
	s_waitcnt vmcnt(11)
	ds_write_b128 v214, v[0:3]
	global_load_dwordx4 v[0:3], v180, s[86:87]
	s_waitcnt lgkmcnt(4)
	v_mfma_f32_16x16x32_bf16 v[92:95], v[216:219], v[244:247], v[92:95]
	v_mfma_f32_16x16x32_bf16 v[88:91], v[220:223], v[244:247], v[88:91]
	v_mfma_f32_16x16x32_bf16 v[84:87], v[224:227], v[244:247], v[84:87]
	v_mfma_f32_16x16x32_bf16 v[80:83], v[228:231], v[244:247], v[80:83]
	ds_read_b128 v[244:247], v242 offset:10240
	s_waitcnt vmcnt(11)
	ds_write_b128 v214, v[4:7] offset:4096
	s_add_u32 s98, s86, 0x40000
	s_addc_u32 s99, s87, 0
	global_load_dwordx4 v[4:7], v180, s[98:99]
	s_waitcnt lgkmcnt(5)
	v_mfma_f32_16x16x32_bf16 v[76:79], v[216:219], v[248:251], v[76:79]
	s_waitcnt lgkmcnt(4)
	v_mfma_f32_16x16x32_bf16 v[60:63], v[216:219], v[252:255], v[60:63]
	ds_read_b128 v[216:219], v243 offset:32768
	v_mfma_f32_16x16x32_bf16 v[72:75], v[220:223], v[248:251], v[72:75]
	v_mfma_f32_16x16x32_bf16 v[56:59], v[220:223], v[252:255], v[56:59]
	ds_read_b128 v[220:223], v243 offset:34816
	v_mfma_f32_16x16x32_bf16 v[68:71], v[224:227], v[248:251], v[68:71]
	v_mfma_f32_16x16x32_bf16 v[52:55], v[224:227], v[252:255], v[52:55]
	ds_read_b128 v[224:227], v243 offset:36864
	v_mfma_f32_16x16x32_bf16 v[64:67], v[228:231], v[248:251], v[64:67]
	v_mfma_f32_16x16x32_bf16 v[48:51], v[228:231], v[252:255], v[48:51]
	ds_read_b128 v[228:231], v243 offset:38912
	ds_read_b128 v[248:251], v242 offset:12288
	ds_read_b128 v[252:255], v242 offset:14336
	s_waitcnt vmcnt(11)
	ds_write_b128 v214, v[16:19] offset:16384
	s_add_u32 s98, s86, 0x100000
	s_addc_u32 s99, s87, 0
	global_load_dwordx4 v[16:19], v180, s[98:99]
	s_waitcnt lgkmcnt(6)
	v_mfma_f32_16x16x32_bf16 v[108:111], v[216:219], v[232:235], v[108:111]
	v_mfma_f32_16x16x32_bf16 v[92:95], v[216:219], v[244:247], v[92:95]
	s_waitcnt lgkmcnt(5)
	v_mfma_f32_16x16x32_bf16 v[104:107], v[220:223], v[232:235], v[104:107]
	v_mfma_f32_16x16x32_bf16 v[88:91], v[220:223], v[244:247], v[88:91]
	s_waitcnt vmcnt(11)
	ds_write_b128 v214, v[20:23] offset:20480
	s_add_u32 s98, s86, 0x140000
	s_addc_u32 s99, s87, 0
	global_load_dwordx4 v[20:23], v180, s[98:99]
	s_waitcnt lgkmcnt(5)
	v_mfma_f32_16x16x32_bf16 v[100:103], v[224:227], v[232:235], v[100:103]
	v_mfma_f32_16x16x32_bf16 v[84:87], v[224:227], v[244:247], v[84:87]
	s_waitcnt lgkmcnt(4)
	v_mfma_f32_16x16x32_bf16 v[96:99], v[228:231], v[232:235], v[96:99]
	v_mfma_f32_16x16x32_bf16 v[80:83], v[228:231], v[244:247], v[80:83]
	s_waitcnt vmcnt(11)
	ds_write_b128 v182, v[40:43] offset:40960
	s_add_u32 s98, s34, 0x80000
	s_addc_u32 s99, s35, 0
	global_load_dwordx4 v[40:43], v180, s[98:99]
	s_waitcnt lgkmcnt(4)
	v_mfma_f32_16x16x32_bf16 v[76:79], v[216:219], v[248:251], v[76:79]
	v_mfma_f32_16x16x32_bf16 v[72:75], v[220:223], v[248:251], v[72:75]
	v_mfma_f32_16x16x32_bf16 v[68:71], v[224:227], v[248:251], v[68:71]
	v_mfma_f32_16x16x32_bf16 v[64:67], v[228:231], v[248:251], v[64:67]
	s_waitcnt vmcnt(11)
	ds_write_b128 v182, v[44:47] offset:45056
	s_add_u32 s98, s34, 0xc0000
	s_addc_u32 s99, s35, 0
	global_load_dwordx4 v[44:47], v180, s[98:99]
	s_waitcnt lgkmcnt(0)
	s_barrier
	v_mfma_f32_16x16x32_bf16 v[60:63], v[216:219], v[252:255], v[60:63]
	v_mfma_f32_16x16x32_bf16 v[56:59], v[220:223], v[252:255], v[56:59]
	v_mfma_f32_16x16x32_bf16 v[52:55], v[224:227], v[252:255], v[52:55]
	v_mfma_f32_16x16x32_bf16 v[48:51], v[228:231], v[252:255], v[48:51]
	v_xor_b32_e32 v176, 0x4000, v176
	v_xor_b32_e32 v243, 0x4000, v243
	v_xor_b32_e32 v182, 0x4000, v182
	s_and_b32 s98, s28, s94
	s_cmp_lg_u32 s98, s28
	s_cbranch_scc0 .Ls_nodrain_ff2
	s_waitcnt vmcnt(0)

.LBB0_41:
	s_cmpk_gt_u32 s33, 0x3bf
	s_cselect_b64 s[28:29], -1, 0
	s_cmp_lg_u32 s33, 0
	s_cbranch_scc1 .Ls_nosetup_ff1
	v_add_u32_e32 v176, v183, v180
	v_add_u32_e32 v243, v183, v213
	v_add_u32_e32 v241, v181, v180
	v_add_u32_e32 v242, v181, v213
	v_or_b32_e32 v183, 0x4000, v214
	v_lshrrev_b32_e32 v180, 3, v184
	v_and_b32_e32 v181, 7, v184
	v_lshlrev_b32_e32 v180, 11, v180
	v_lshl_add_u32 v180, v181, 4, v180
	s_cmp_eq_u32 s100, 0
	s_cbranch_scc1 .Ls_nosetup_ff1
	s_mov_b32 s100, 0
	s_waitcnt vmcnt(0)
	ds_write_b128 v214, v[0:3]
	ds_write_b128 v214, v[4:7] offset:4096
	ds_write_b128 v214, v[16:19] offset:16384
	ds_write_b128 v214, v[20:23] offset:20480
	ds_write_b128 v214, v[32:35] offset:32768
	ds_write_b128 v214, v[36:39] offset:36864
	ds_write_b128 v214, v[40:43] offset:40960
	ds_write_b128 v214, v[44:47] offset:45056
	s_movk_i32 s101, 0x80
	s_add_u32 s86, s46, s101
	s_addc_u32 s87, s47, 0
	s_add_u32 s34, s50, s101
	s_addc_u32 s35, s51, 0
	global_load_dwordx4 v[32:35], v180, s[34:35]
	s_add_u32 s98, s34, 0x10000
	s_addc_u32 s99, s35, 0
	global_load_dwordx4 v[36:39], v180, s[98:99]
	global_load_dwordx4 v[0:3], v180, s[86:87]
	s_add_u32 s98, s86, 0x10000
	s_addc_u32 s99, s87, 0
	global_load_dwordx4 v[4:7], v180, s[98:99]
	s_add_u32 s98, s86, 0x40000
	s_addc_u32 s99, s87, 0
	global_load_dwordx4 v[16:19], v180, s[98:99]
	s_add_u32 s98, s86, 0x50000
	s_addc_u32 s99, s87, 0
	global_load_dwordx4 v[20:23], v180, s[98:99]
	s_add_u32 s98, s34, 0x20000
	s_addc_u32 s99, s35, 0
	global_load_dwordx4 v[40:43], v180, s[98:99]
	s_add_u32 s98, s34, 0x30000
	s_addc_u32 s99, s35, 0
	global_load_dwordx4 v[44:47], v180, s[98:99]
	s_waitcnt lgkmcnt(0)
	s_barrier
.Ls_nosetup_ff1:
	s_add_i32 s101, s33, 64
	s_cmpk_ge_u32 s101, 0x400
	s_cselect_b32 s98, 0x400, 0
	s_cselect_b32 s99, s92, 0
	s_sub_u32 s101, s101, s98
	s_lshl_b32 s101, s101, 1
	s_cmp_lg_u32 s99, 0
	s_cselect_b64 s[84:85], s[36:37], s[46:47]
	s_add_u32 s84, s84, s101
	s_addc_u32 s85, s85, 0
	s_add_i32 s101, s33, 128
	s_cmpk_ge_u32 s101, 0x400
	s_cselect_b32 s98, 0x400, 0
	s_cselect_b32 s99, s92, 0
	s_sub_u32 s101, s101, s98
	s_lshl_b32 s101, s101, 1
	s_cmp_lg_u32 s99, 0
	s_cselect_b64 s[86:87], s[36:37], s[46:47]
	s_cselect_b64 s[34:35], s[38:39], s[50:51]
	s_add_u32 s86, s86, s101
	s_addc_u32 s87, s87, 0
	s_add_u32 s34, s34, s101
	s_addc_u32 s35, s35, 0
	ds_read_b128 v[216:219], v176 offset:32768
	ds_read_b128 v[232:235], v241
	ds_read_b128 v[220:223], v176 offset:34816
	ds_read_b128 v[224:227], v176 offset:36864
	ds_read_b128 v[228:231], v176 offset:38912
	ds_read_b128 v[244:247], v241 offset:2048
	ds_read_b128 v[248:251], v241 offset:4096
	ds_read_b128 v[252:255], v241 offset:6144
	s_waitcnt lgkmcnt(6)
	v_mfma_f32_16x16x32_bf16 v[172:175], v[216:219], v[232:235], v[172:175]
	s_waitcnt lgkmcnt(5)
	v_mfma_f32_16x16x32_bf16 v[168:171], v[220:223], v[232:235], v[168:171]
	s_waitcnt lgkmcnt(4)
	v_mfma_f32_16x16x32_bf16 v[164:167], v[224:227], v[232:235], v[164:167]
	s_waitcnt lgkmcnt(3)
	v_mfma_f32_16x16x32_bf16 v[160:163], v[228:231], v[232:235], v[160:163]
	ds_read_b128 v[232:235], v242
	s_waitcnt vmcnt(11)
	ds_write_b128 v214, v[8:11] offset:8192
	s_add_u32 s98, s84, 0x20000
	s_addc_u32 s99, s85, 0
	global_load_dwordx4 v[8:11], v180, s[98:99]
	s_waitcnt lgkmcnt(4)
	v_mfma_f32_16x16x32_bf16 v[156:159], v[216:219], v[244:247], v[156:159]
	v_mfma_f32_16x16x32_bf16 v[152:155], v[220:223], v[244:247], v[152:155]
	v_mfma_f32_16x16x32_bf16 v[148:151], v[224:227], v[244:247], v[148:151]
	v_mfma_f32_16x16x32_bf16 v[144:147], v[228:231], v[244:247], v[144:147]
	ds_read_b128 v[244:247], v242 offset:2048
	s_waitcnt vmcnt(11)
	ds_write_b128 v214, v[12:15] offset:12288
	s_add_u32 s98, s84, 0x30000
	s_addc_u32 s99, s85, 0
	global_load_dwordx4 v[12:15], v180, s[98:99]
	s_waitcnt lgkmcnt(5)
	v_mfma_f32_16x16x32_bf16 v[140:143], v[216:219], v[248:251], v[140:143]
	s_waitcnt lgkmcnt(4)
	v_mfma_f32_16x16x32_bf16 v[124:127], v[216:219], v[252:255], v[124:127]
	ds_read_b128 v[216:219], v243 offset:32768
	v_mfma_f32_16x16x32_bf16 v[136:139], v[220:223], v[248:251], v[136:139]
	v_mfma_f32_16x16x32_bf16 v[120:123], v[220:223], v[252:255], v[120:123]
	ds_read_b128 v[220:223], v243 offset:34816
	v_mfma_f32_16x16x32_bf16 v[132:135], v[224:227], v[248:251], v[132:135]
	v_mfma_f32_16x16x32_bf16 v[116:119], v[224:227], v[252:255], v[116:119]
	ds_read_b128 v[224:227], v243 offset:36864
	v_mfma_f32_16x16x32_bf16 v[128:131], v[228:231], v[248:251], v[128:131]
	v_mfma_f32_16x16x32_bf16 v[112:115], v[228:231], v[252:255], v[112:115]
	ds_read_b128 v[228:231], v243 offset:38912
	ds_read_b128 v[248:251], v242 offset:4096
	ds_read_b128 v[252:255], v242 offset:6144
	s_waitcnt vmcnt(11)
	ds_write_b128 v214, v[24:27] offset:24576
	s_add_u32 s98, s84, 0x60000
	s_addc_u32 s99, s85, 0
	global_load_dwordx4 v[24:27], v180, s[98:99]
	s_waitcnt lgkmcnt(6)
	v_mfma_f32_16x16x32_bf16 v[172:175], v[216:219], v[232:235], v[172:175]
	v_mfma_f32_16x16x32_bf16 v[156:159], v[216:219], v[244:247], v[156:159]
	s_waitcnt lgkmcnt(5)
	v_mfma_f32_16x16x32_bf16 v[168:171], v[220:223], v[232:235], v[168:171]
	v_mfma_f32_16x16x32_bf16 v[152:155], v[220:223], v[244:247], v[152:155]
	s_waitcnt vmcnt(11)
	ds_write_b128 v214, v[28:31] offset:28672
	s_add_u32 s98, s84, 0x70000
	s_addc_u32 s99, s85, 0
	global_load_dwordx4 v[28:31], v180, s[98:99]
	s_waitcnt lgkmcnt(5)
	v_mfma_f32_16x16x32_bf16 v[164:167], v[224:227], v[232:235], v[164:167]
	v_mfma_f32_16x16x32_bf16 v[148:151], v[224:227], v[244:247], v[148:151]
	s_waitcnt lgkmcnt(4)
	v_mfma_f32_16x16x32_bf16 v[160:163], v[228:231], v[232:235], v[160:163]
	v_mfma_f32_16x16x32_bf16 v[144:147], v[228:231], v[244:247], v[144:147]
	s_waitcnt vmcnt(11)
	ds_write_b128 v183, v[32:35] offset:32768
	global_load_dwordx4 v[32:35], v180, s[34:35]
	s_waitcnt lgkmcnt(4)
	v_mfma_f32_16x16x32_bf16 v[140:143], v[216:219], v[248:251], v[140:143]
	v_mfma_f32_16x16x32_bf16 v[136:139], v[220:223], v[248:251], v[136:139]
	v_mfma_f32_16x16x32_bf16 v[132:135], v[224:227], v[248:251], v[132:135]
	v_mfma_f32_16x16x32_bf16 v[128:131], v[228:231], v[248:251], v[128:131]
	s_waitcnt vmcnt(11)
	ds_write_b128 v183, v[36:39] offset:36864
	s_add_u32 s98, s34, 0x10000
	s_addc_u32 s99, s35, 0
	global_load_dwordx4 v[36:39], v180, s[98:99]
	s_waitcnt lgkmcnt(0)
	s_barrier
	v_mfma_f32_16x16x32_bf16 v[124:127], v[216:219], v[252:255], v[124:127]
	v_mfma_f32_16x16x32_bf16 v[120:123], v[220:223], v[252:255], v[120:123]
	v_mfma_f32_16x16x32_bf16 v[116:119], v[224:227], v[252:255], v[116:119]
	v_mfma_f32_16x16x32_bf16 v[112:115], v[228:231], v[252:255], v[112:115]
	ds_read_b128 v[216:219], v176 offset:32768
	ds_read_b128 v[232:235], v241 offset:8192
	ds_read_b128 v[220:223], v176 offset:34816
	ds_read_b128 v[224:227], v176 offset:36864
	ds_read_b128 v[228:231], v176 offset:38912
	ds_read_b128 v[244:247], v241 offset:10240
	ds_read_b128 v[248:251], v241 offset:12288
	ds_read_b128 v[252:255], v241 offset:14336
	s_waitcnt lgkmcnt(6)
	v_mfma_f32_16x16x32_bf16 v[108:111], v[216:219], v[232:235], v[108:111]
	s_waitcnt lgkmcnt(5)
	v_mfma_f32_16x16x32_bf16 v[104:107], v[220:223], v[232:235], v[104:107]
	s_waitcnt lgkmcnt(4)
	v_mfma_f32_16x16x32_bf16 v[100:103], v[224:227], v[232:235], v[100:103]
	s_waitcnt lgkmcnt(3)
	v_mfma_f32_16x16x32_bf16 v[96:99], v[228:231], v[232:235], v[96:99]
	ds_read_b128 v[232:235], v242 offset:8192
	s_waitcnt vmcnt(11)
	ds_write_b128 v214, v[0:3]
	global_load_dwordx4 v[0:3], v180, s[86:87]
	s_waitcnt lgkmcnt(4)
	v_mfma_f32_16x16x32_bf16 v[92:95], v[216:219], v[244:247], v[92:95]
	v_mfma_f32_16x16x32_bf16 v[88:91], v[220:223], v[244:247], v[88:91]
	v_mfma_f32_16x16x32_bf16 v[84:87], v[224:227], v[244:247], v[84:87]
	v_mfma_f32_16x16x32_bf16 v[80:83], v[228:231], v[244:247], v[80:83]
	ds_read_b128 v[244:247], v242 offset:10240
	s_waitcnt vmcnt(11)
	ds_write_b128 v214, v[4:7] offset:4096
	s_add_u32 s98, s86, 0x10000
	s_addc_u32 s99, s87, 0
	global_load_dwordx4 v[4:7], v180, s[98:99]
	s_waitcnt lgkmcnt(5)
	v_mfma_f32_16x16x32_bf16 v[76:79], v[216:219], v[248:251], v[76:79]
	s_waitcnt lgkmcnt(4)
	v_mfma_f32_16x16x32_bf16 v[60:63], v[216:219], v[252:255], v[60:63]
	ds_read_b128 v[216:219], v243 offset:32768
	v_mfma_f32_16x16x32_bf16 v[72:75], v[220:223], v[248:251], v[72:75]
	v_mfma_f32_16x16x32_bf16 v[56:59], v[220:223], v[252:255], v[56:59]
	ds_read_b128 v[220:223], v243 offset:34816
	v_mfma_f32_16x16x32_bf16 v[68:71], v[224:227], v[248:251], v[68:71]
	v_mfma_f32_16x16x32_bf16 v[52:55], v[224:227], v[252:255], v[52:55]
	ds_read_b128 v[224:227], v243 offset:36864
	v_mfma_f32_16x16x32_bf16 v[64:67], v[228:231], v[248:251], v[64:67]
	v_mfma_f32_16x16x32_bf16 v[48:51], v[228:231], v[252:255], v[48:51]
	ds_read_b128 v[228:231], v243 offset:38912
	ds_read_b128 v[248:251], v242 offset:12288
	ds_read_b128 v[252:255], v242 offset:14336
	s_waitcnt vmcnt(11)
	ds_write_b128 v214, v[16:19] offset:16384
	s_add_u32 s98, s86, 0x40000
	s_addc_u32 s99, s87, 0
	global_load_dwordx4 v[16:19], v180, s[98:99]
	s_waitcnt lgkmcnt(6)
	v_mfma_f32_16x16x32_bf16 v[108:111], v[216:219], v[232:235], v[108:111]
	v_mfma_f32_16x16x32_bf16 v[92:95], v[216:219], v[244:247], v[92:95]
	s_waitcnt lgkmcnt(5)
	v_mfma_f32_16x16x32_bf16 v[104:107], v[220:223], v[232:235], v[104:107]
	v_mfma_f32_16x16x32_bf16 v[88:91], v[220:223], v[244:247], v[88:91]
	s_waitcnt vmcnt(11)
	ds_write_b128 v214, v[20:23] offset:20480
	s_add_u32 s98, s86, 0x50000
	s_addc_u32 s99, s87, 0
	global_load_dwordx4 v[20:23], v180, s[98:99]
	s_waitcnt lgkmcnt(5)
	v_mfma_f32_16x16x32_bf16 v[100:103], v[224:227], v[232:235], v[100:103]
	v_mfma_f32_16x16x32_bf16 v[84:87], v[224:227], v[244:247], v[84:87]
	s_waitcnt lgkmcnt(4)
	v_mfma_f32_16x16x32_bf16 v[96:99], v[228:231], v[232:235], v[96:99]
	v_mfma_f32_16x16x32_bf16 v[80:83], v[228:231], v[244:247], v[80:83]
	s_waitcnt vmcnt(11)
	ds_write_b128 v183, v[40:43] offset:40960
	s_add_u32 s98, s34, 0x20000
	s_addc_u32 s99, s35, 0
	global_load_dwordx4 v[40:43], v180, s[98:99]
	s_waitcnt lgkmcnt(4)
	v_mfma_f32_16x16x32_bf16 v[76:79], v[216:219], v[248:251], v[76:79]
	v_mfma_f32_16x16x32_bf16 v[72:75], v[220:223], v[248:251], v[72:75]
	v_mfma_f32_16x16x32_bf16 v[68:71], v[224:227], v[248:251], v[68:71]
	v_mfma_f32_16x16x32_bf16 v[64:67], v[228:231], v[248:251], v[64:67]
	s_waitcnt vmcnt(11)
	ds_write_b128 v183, v[44:47] offset:45056
	s_add_u32 s98, s34, 0x30000
	s_addc_u32 s99, s35, 0
	global_load_dwordx4 v[44:47], v180, s[98:99]
	s_waitcnt lgkmcnt(0)
	s_barrier
	v_mfma_f32_16x16x32_bf16 v[60:63], v[216:219], v[252:255], v[60:63]
	v_mfma_f32_16x16x32_bf16 v[56:59], v[220:223], v[252:255], v[56:59]
	v_mfma_f32_16x16x32_bf16 v[52:55], v[224:227], v[252:255], v[52:55]
	v_mfma_f32_16x16x32_bf16 v[48:51], v[228:231], v[252:255], v[48:51]
	v_xor_b32_e32 v176, 0x4000, v176
	v_xor_b32_e32 v243, 0x4000, v243
	v_xor_b32_e32 v183, 0x4000, v183
	s_and_b32 s98, s28, s92
	s_cmp_lg_u32 s98, s28
	s_cbranch_scc0 .Ls_nodrain_ff1
	s_waitcnt vmcnt(0)

.LBB0_66:
	s_cmpk_gt_u32 s33, 0x3bf
	s_cselect_b64 s[28:29], -1, 0
	s_cmp_lg_u32 s33, 0
	s_cbranch_scc1 .Ls_nosetup_wout
	v_add_u32_e32 v176, v182, v180
	v_add_u32_e32 v243, v182, v183
	v_add_u32_e32 v241, v181, v180
	v_add_u32_e32 v242, v181, v183
	v_or_b32_e32 v182, 0x4000, v214
	v_lshrrev_b32_e32 v180, 3, v184
	v_and_b32_e32 v181, 7, v184
	v_lshlrev_b32_e32 v180, 11, v180
	v_lshl_add_u32 v180, v181, 4, v180
	s_cmp_eq_u32 s100, 0
	s_cbranch_scc1 .Ls_nosetup_wout
	s_mov_b32 s100, 0
	s_waitcnt vmcnt(0)
	ds_write_b128 v214, v[0:3]
	ds_write_b128 v214, v[4:7] offset:4096
	ds_write_b128 v214, v[16:19] offset:16384
	ds_write_b128 v214, v[20:23] offset:20480
	ds_write_b128 v214, v[32:35] offset:32768
	ds_write_b128 v214, v[36:39] offset:36864
	ds_write_b128 v214, v[40:43] offset:40960
	ds_write_b128 v214, v[44:47] offset:45056
	s_movk_i32 s101, 0x80
	s_add_u32 s86, s50, s101
	s_addc_u32 s87, s51, 0
	s_add_u32 s34, s92, s101
	s_addc_u32 s35, s93, 0
	global_load_dwordx4 v[32:35], v180, s[34:35]
	s_add_u32 s98, s34, 0x10000
	s_addc_u32 s99, s35, 0
	global_load_dwordx4 v[36:39], v180, s[98:99]
	global_load_dwordx4 v[0:3], v180, s[86:87]
	s_add_u32 s98, s86, 0x10000
	s_addc_u32 s99, s87, 0
	global_load_dwordx4 v[4:7], v180, s[98:99]
	s_add_u32 s98, s86, 0x40000
	s_addc_u32 s99, s87, 0
	global_load_dwordx4 v[16:19], v180, s[98:99]
	s_add_u32 s98, s86, 0x50000
	s_addc_u32 s99, s87, 0
	global_load_dwordx4 v[20:23], v180, s[98:99]
	s_add_u32 s98, s34, 0x20000
	s_addc_u32 s99, s35, 0
	global_load_dwordx4 v[40:43], v180, s[98:99]
	s_add_u32 s98, s34, 0x30000
	s_addc_u32 s99, s35, 0
	global_load_dwordx4 v[44:47], v180, s[98:99]
	s_waitcnt lgkmcnt(0)
	s_barrier
.Ls_nosetup_wout:
	s_add_i32 s101, s33, 64
	s_cmpk_ge_u32 s101, 0x400
	s_cselect_b32 s98, 0x400, 0
	s_cselect_b32 s99, s94, 0
	s_sub_u32 s101, s101, s98
	s_lshl_b32 s101, s101, 1
	s_cmp_lg_u32 s99, 0
	s_cselect_b64 s[84:85], s[40:41], s[50:51]
	s_add_u32 s84, s84, s101
	s_addc_u32 s85, s85, 0
	s_add_i32 s101, s33, 128
	s_cmpk_ge_u32 s101, 0x400
	s_cselect_b32 s98, 0x400, 0
	s_cselect_b32 s99, s94, 0
	s_sub_u32 s101, s101, s98
	s_lshl_b32 s101, s101, 1
	s_cmp_lg_u32 s99, 0
	s_cselect_b64 s[86:87], s[40:41], s[50:51]
	s_cselect_b64 s[34:35], s[42:43], s[92:93]
	s_add_u32 s86, s86, s101
	s_addc_u32 s87, s87, 0
	s_add_u32 s34, s34, s101
	s_addc_u32 s35, s35, 0
	ds_read_b128 v[216:219], v176 offset:32768
	ds_read_b128 v[232:235], v241
	ds_read_b128 v[220:223], v176 offset:34816
	ds_read_b128 v[224:227], v176 offset:36864
	ds_read_b128 v[228:231], v176 offset:38912
	ds_read_b128 v[244:247], v241 offset:2048
	ds_read_b128 v[248:251], v241 offset:4096
	ds_read_b128 v[252:255], v241 offset:6144
	s_waitcnt lgkmcnt(6)
	v_mfma_f32_16x16x32_bf16 v[172:175], v[216:219], v[232:235], v[172:175]
	s_waitcnt lgkmcnt(5)
	v_mfma_f32_16x16x32_bf16 v[168:171], v[220:223], v[232:235], v[168:171]
	s_waitcnt lgkmcnt(4)
	v_mfma_f32_16x16x32_bf16 v[164:167], v[224:227], v[232:235], v[164:167]
	s_waitcnt lgkmcnt(3)
	v_mfma_f32_16x16x32_bf16 v[160:163], v[228:231], v[232:235], v[160:163]
	ds_read_b128 v[232:235], v242
	s_waitcnt vmcnt(11)
	ds_write_b128 v214, v[8:11] offset:8192
	s_add_u32 s98, s84, 0x20000
	s_addc_u32 s99, s85, 0
	global_load_dwordx4 v[8:11], v180, s[98:99]
	s_waitcnt lgkmcnt(4)
	v_mfma_f32_16x16x32_bf16 v[156:159], v[216:219], v[244:247], v[156:159]
	v_mfma_f32_16x16x32_bf16 v[152:155], v[220:223], v[244:247], v[152:155]
	v_mfma_f32_16x16x32_bf16 v[148:151], v[224:227], v[244:247], v[148:151]
	v_mfma_f32_16x16x32_bf16 v[144:147], v[228:231], v[244:247], v[144:147]
	ds_read_b128 v[244:247], v242 offset:2048
	s_waitcnt vmcnt(11)
	ds_write_b128 v214, v[12:15] offset:12288
	s_add_u32 s98, s84, 0x30000
	s_addc_u32 s99, s85, 0
	global_load_dwordx4 v[12:15], v180, s[98:99]
	s_waitcnt lgkmcnt(5)
	v_mfma_f32_16x16x32_bf16 v[140:143], v[216:219], v[248:251], v[140:143]
	s_waitcnt lgkmcnt(4)
	v_mfma_f32_16x16x32_bf16 v[124:127], v[216:219], v[252:255], v[124:127]
	ds_read_b128 v[216:219], v243 offset:32768
	v_mfma_f32_16x16x32_bf16 v[136:139], v[220:223], v[248:251], v[136:139]
	v_mfma_f32_16x16x32_bf16 v[120:123], v[220:223], v[252:255], v[120:123]
	ds_read_b128 v[220:223], v243 offset:34816
	v_mfma_f32_16x16x32_bf16 v[132:135], v[224:227], v[248:251], v[132:135]
	v_mfma_f32_16x16x32_bf16 v[116:119], v[224:227], v[252:255], v[116:119]
	ds_read_b128 v[224:227], v243 offset:36864
	v_mfma_f32_16x16x32_bf16 v[128:131], v[228:231], v[248:251], v[128:131]
	v_mfma_f32_16x16x32_bf16 v[112:115], v[228:231], v[252:255], v[112:115]
	ds_read_b128 v[228:231], v243 offset:38912
	ds_read_b128 v[248:251], v242 offset:4096
	ds_read_b128 v[252:255], v242 offset:6144
	s_waitcnt vmcnt(11)
	ds_write_b128 v214, v[24:27] offset:24576
	s_add_u32 s98, s84, 0x60000
	s_addc_u32 s99, s85, 0
	global_load_dwordx4 v[24:27], v180, s[98:99]
	s_waitcnt lgkmcnt(6)
	v_mfma_f32_16x16x32_bf16 v[172:175], v[216:219], v[232:235], v[172:175]
	v_mfma_f32_16x16x32_bf16 v[156:159], v[216:219], v[244:247], v[156:159]
	s_waitcnt lgkmcnt(5)
	v_mfma_f32_16x16x32_bf16 v[168:171], v[220:223], v[232:235], v[168:171]
	v_mfma_f32_16x16x32_bf16 v[152:155], v[220:223], v[244:247], v[152:155]
	s_waitcnt vmcnt(11)
	ds_write_b128 v214, v[28:31] offset:28672
	s_add_u32 s98, s84, 0x70000
	s_addc_u32 s99, s85, 0
	global_load_dwordx4 v[28:31], v180, s[98:99]
	s_waitcnt lgkmcnt(5)
	v_mfma_f32_16x16x32_bf16 v[164:167], v[224:227], v[232:235], v[164:167]
	v_mfma_f32_16x16x32_bf16 v[148:151], v[224:227], v[244:247], v[148:151]
	s_waitcnt lgkmcnt(4)
	v_mfma_f32_16x16x32_bf16 v[160:163], v[228:231], v[232:235], v[160:163]
	v_mfma_f32_16x16x32_bf16 v[144:147], v[228:231], v[244:247], v[144:147]
	s_waitcnt vmcnt(11)
	ds_write_b128 v182, v[32:35] offset:32768
	global_load_dwordx4 v[32:35], v180, s[34:35]
	s_waitcnt lgkmcnt(4)
	v_mfma_f32_16x16x32_bf16 v[140:143], v[216:219], v[248:251], v[140:143]
	v_mfma_f32_16x16x32_bf16 v[136:139], v[220:223], v[248:251], v[136:139]
	v_mfma_f32_16x16x32_bf16 v[132:135], v[224:227], v[248:251], v[132:135]
	v_mfma_f32_16x16x32_bf16 v[128:131], v[228:231], v[248:251], v[128:131]
	s_waitcnt vmcnt(11)
	ds_write_b128 v182, v[36:39] offset:36864
	s_add_u32 s98, s34, 0x10000
	s_addc_u32 s99, s35, 0
	global_load_dwordx4 v[36:39], v180, s[98:99]
	s_waitcnt lgkmcnt(0)
	s_barrier
	v_mfma_f32_16x16x32_bf16 v[124:127], v[216:219], v[252:255], v[124:127]
	v_mfma_f32_16x16x32_bf16 v[120:123], v[220:223], v[252:255], v[120:123]
	v_mfma_f32_16x16x32_bf16 v[116:119], v[224:227], v[252:255], v[116:119]
	v_mfma_f32_16x16x32_bf16 v[112:115], v[228:231], v[252:255], v[112:115]
	ds_read_b128 v[216:219], v176 offset:32768
	ds_read_b128 v[232:235], v241 offset:8192
	ds_read_b128 v[220:223], v176 offset:34816
	ds_read_b128 v[224:227], v176 offset:36864
	ds_read_b128 v[228:231], v176 offset:38912
	ds_read_b128 v[244:247], v241 offset:10240
	ds_read_b128 v[248:251], v241 offset:12288
	ds_read_b128 v[252:255], v241 offset:14336
	s_waitcnt lgkmcnt(6)
	v_mfma_f32_16x16x32_bf16 v[108:111], v[216:219], v[232:235], v[108:111]
	s_waitcnt lgkmcnt(5)
	v_mfma_f32_16x16x32_bf16 v[104:107], v[220:223], v[232:235], v[104:107]
	s_waitcnt lgkmcnt(4)
	v_mfma_f32_16x16x32_bf16 v[100:103], v[224:227], v[232:235], v[100:103]
	s_waitcnt lgkmcnt(3)
	v_mfma_f32_16x16x32_bf16 v[96:99], v[228:231], v[232:235], v[96:99]
	ds_read_b128 v[232:235], v242 offset:8192
	s_waitcnt vmcnt(11)
	ds_write_b128 v214, v[0:3]
	global_load_dwordx4 v[0:3], v180, s[86:87]
	s_waitcnt lgkmcnt(4)
	v_mfma_f32_16x16x32_bf16 v[92:95], v[216:219], v[244:247], v[92:95]
	v_mfma_f32_16x16x32_bf16 v[88:91], v[220:223], v[244:247], v[88:91]
	v_mfma_f32_16x16x32_bf16 v[84:87], v[224:227], v[244:247], v[84:87]
	v_mfma_f32_16x16x32_bf16 v[80:83], v[228:231], v[244:247], v[80:83]
	ds_read_b128 v[244:247], v242 offset:10240
	s_waitcnt vmcnt(11)
	ds_write_b128 v214, v[4:7] offset:4096
	s_add_u32 s98, s86, 0x10000
	s_addc_u32 s99, s87, 0
	global_load_dwordx4 v[4:7], v180, s[98:99]
	s_waitcnt lgkmcnt(5)
	v_mfma_f32_16x16x32_bf16 v[76:79], v[216:219], v[248:251], v[76:79]
	s_waitcnt lgkmcnt(4)
	v_mfma_f32_16x16x32_bf16 v[60:63], v[216:219], v[252:255], v[60:63]
	ds_read_b128 v[216:219], v243 offset:32768
	v_mfma_f32_16x16x32_bf16 v[72:75], v[220:223], v[248:251], v[72:75]
	v_mfma_f32_16x16x32_bf16 v[56:59], v[220:223], v[252:255], v[56:59]
	ds_read_b128 v[220:223], v243 offset:34816
	v_mfma_f32_16x16x32_bf16 v[68:71], v[224:227], v[248:251], v[68:71]
	v_mfma_f32_16x16x32_bf16 v[52:55], v[224:227], v[252:255], v[52:55]
	ds_read_b128 v[224:227], v243 offset:36864
	v_mfma_f32_16x16x32_bf16 v[64:67], v[228:231], v[248:251], v[64:67]
	v_mfma_f32_16x16x32_bf16 v[48:51], v[228:231], v[252:255], v[48:51]
	ds_read_b128 v[228:231], v243 offset:38912
	ds_read_b128 v[248:251], v242 offset:12288
	ds_read_b128 v[252:255], v242 offset:14336
	s_waitcnt vmcnt(11)
	ds_write_b128 v214, v[16:19] offset:16384
	s_add_u32 s98, s86, 0x40000
	s_addc_u32 s99, s87, 0
	global_load_dwordx4 v[16:19], v180, s[98:99]
	s_waitcnt lgkmcnt(6)
	v_mfma_f32_16x16x32_bf16 v[108:111], v[216:219], v[232:235], v[108:111]
	v_mfma_f32_16x16x32_bf16 v[92:95], v[216:219], v[244:247], v[92:95]
	s_waitcnt lgkmcnt(5)
	v_mfma_f32_16x16x32_bf16 v[104:107], v[220:223], v[232:235], v[104:107]
	v_mfma_f32_16x16x32_bf16 v[88:91], v[220:223], v[244:247], v[88:91]
	s_waitcnt vmcnt(11)
	ds_write_b128 v214, v[20:23] offset:20480
	s_add_u32 s98, s86, 0x50000
	s_addc_u32 s99, s87, 0
	global_load_dwordx4 v[20:23], v180, s[98:99]
	s_waitcnt lgkmcnt(5)
	v_mfma_f32_16x16x32_bf16 v[100:103], v[224:227], v[232:235], v[100:103]
	v_mfma_f32_16x16x32_bf16 v[84:87], v[224:227], v[244:247], v[84:87]
	s_waitcnt lgkmcnt(4)
	v_mfma_f32_16x16x32_bf16 v[96:99], v[228:231], v[232:235], v[96:99]
	v_mfma_f32_16x16x32_bf16 v[80:83], v[228:231], v[244:247], v[80:83]
	s_waitcnt vmcnt(11)
	ds_write_b128 v182, v[40:43] offset:40960
	s_add_u32 s98, s34, 0x20000
	s_addc_u32 s99, s35, 0
	global_load_dwordx4 v[40:43], v180, s[98:99]
	s_waitcnt lgkmcnt(4)
	v_mfma_f32_16x16x32_bf16 v[76:79], v[216:219], v[248:251], v[76:79]
	v_mfma_f32_16x16x32_bf16 v[72:75], v[220:223], v[248:251], v[72:75]
	v_mfma_f32_16x16x32_bf16 v[68:71], v[224:227], v[248:251], v[68:71]
	v_mfma_f32_16x16x32_bf16 v[64:67], v[228:231], v[248:251], v[64:67]
	s_waitcnt vmcnt(11)
	ds_write_b128 v182, v[44:47] offset:45056
	s_add_u32 s98, s34, 0x30000
	s_addc_u32 s99, s35, 0
	global_load_dwordx4 v[44:47], v180, s[98:99]
	s_waitcnt lgkmcnt(0)
	s_barrier
	v_mfma_f32_16x16x32_bf16 v[60:63], v[216:219], v[252:255], v[60:63]
	v_mfma_f32_16x16x32_bf16 v[56:59], v[220:223], v[252:255], v[56:59]
	v_mfma_f32_16x16x32_bf16 v[52:55], v[224:227], v[252:255], v[52:55]
	v_mfma_f32_16x16x32_bf16 v[48:51], v[228:231], v[252:255], v[48:51]
	v_xor_b32_e32 v176, 0x4000, v176
	v_xor_b32_e32 v243, 0x4000, v243
	v_xor_b32_e32 v182, 0x4000, v182
	s_and_b32 s98, s28, s94
	s_cmp_lg_u32 s98, s28
	s_cbranch_scc0 .Ls_nodrain_wout
	s_waitcnt vmcnt(0)

.LBB0_81:
	s_mul_i32 s26, s17, s40
	s_mul_hi_u32 s28, s16, s40
	s_add_i32 s28, s28, s26
	s_mul_i32 s26, s16, s40
	s_mov_b32 s41, s27
	s_add_u32 s34, s24, s26
	s_addc_u32 s35, s25, s28
	s_lshl_b64 s[28:29], s[40:41], 10
	s_add_u32 s46, s28, s37
	s_addc_u32 s47, s29, s33
	v_readlane_b32 s0, v239, 18
	s_lshl_b64 s[28:29], s[46:47], 11
	v_readlane_b32 s8, v239, 26
	v_mov_b32_e32 v32, v184
	v_readlane_b32 s9, v239, 27
	s_add_u32 s28, s8, s28
	v_readlane_b32 s48, v239, 34
	s_movk_i32 s0, 0x70
	v_lshlrev_b32_e32 v34, 4, v32
	s_waitcnt vmcnt(42)
	v_lshlrev_b32_e32 v36, 3, v32
	v_and_b32_e32 v37, 48, v32
	s_addc_u32 s29, s9, s29
	s_lshl_b64 s[46:47], s[46:47], 10
	v_readlane_b32 s50, v239, 36
	v_readlane_b32 s52, v239, 38
	v_and_b32_e32 v33, 15, v32
	v_and_b32_e32 v35, 0xffffff80, v34
	v_bitop3_b32 v34, v34, s0, v32 bitop3:0x48
	v_bitop3_b32 v166, v36, v37, s0 bitop3:0x6c
	v_lshrrev_b32_e32 v36, 1, v32
	s_mov_b32 s0, 0x1ffffc0
	v_readlane_b32 s51, v239, 37
	v_readlane_b32 s53, v239, 39
	s_add_u32 s50, s52, s46
	v_and_or_b32 v33, v36, s0, v33
	v_lshlrev_b32_e32 v32, 7, v32
	s_addc_u32 s51, s53, s47
	v_lshlrev_b32_e32 v167, 7, v33
	v_and_b32_e32 v168, 0x2780, v32
	v_xor_b32_e32 v169, 64, v166
	v_add_u32_e32 v170, v35, v34
	s_mov_b32 s41, 0
	v_mov_b32_e32 v32, 0
	v_mov_b32_e32 v33, v165
	v_mov_b32_e32 v34, v165
	v_mov_b32_e32 v35, v165
	v_mov_b32_e32 v36, 0
	v_mov_b32_e32 v37, v165
	v_mov_b32_e32 v38, v165
	v_mov_b32_e32 v39, v165
	s_waitcnt vmcnt(41)
	v_mov_b32_e32 v40, 0
	v_mov_b32_e32 v41, v165
	v_mov_b32_e32 v42, v165
	v_mov_b32_e32 v43, v165
	s_waitcnt vmcnt(40)
	v_mov_b32_e32 v44, 0
	v_mov_b32_e32 v45, v165
	v_mov_b32_e32 v46, v165
	v_mov_b32_e32 v47, v165
	v_mov_b32_e32 v48, 0
	v_mov_b32_e32 v49, v165
	v_mov_b32_e32 v50, v165
	v_mov_b32_e32 v51, v165
	v_mov_b32_e32 v52, 0
	v_mov_b32_e32 v53, v165
	v_mov_b32_e32 v54, v165
	v_mov_b32_e32 v55, v165
	v_mov_b32_e32 v56, 0
	v_mov_b32_e32 v57, v165
	v_mov_b32_e32 v58, v165
	v_mov_b32_e32 v59, v165
	v_mov_b32_e32 v60, 0
	v_mov_b32_e32 v61, v165
	v_mov_b32_e32 v62, v165
	v_mov_b32_e32 v63, v165
	v_mov_b32_e32 v64, 0
	v_mov_b32_e32 v65, v165
	v_mov_b32_e32 v66, v165
	v_mov_b32_e32 v67, v165
	v_mov_b32_e32 v68, 0
	v_mov_b32_e32 v69, v165
	v_mov_b32_e32 v70, v165
	v_mov_b32_e32 v71, v165
	v_mov_b32_e32 v72, 0
	v_mov_b32_e32 v73, v165
	v_mov_b32_e32 v74, v165
	v_mov_b32_e32 v75, v165
	v_mov_b32_e32 v76, 0
	v_mov_b32_e32 v77, v165
	v_mov_b32_e32 v78, v165
	v_mov_b32_e32 v79, v165
	v_mov_b32_e32 v80, 0
	v_mov_b32_e32 v81, v165
	v_mov_b32_e32 v82, v165
	v_mov_b32_e32 v83, v165
	v_mov_b32_e32 v84, 0
	v_mov_b32_e32 v85, v165
	v_mov_b32_e32 v86, v165
	v_mov_b32_e32 v87, v165
	v_mov_b32_e32 v88, 0
	v_mov_b32_e32 v89, v165
	v_mov_b32_e32 v90, v165
	v_mov_b32_e32 v91, v165
	v_mov_b32_e32 v92, 0
	v_mov_b32_e32 v93, v165
	v_mov_b32_e32 v94, v165
	v_mov_b32_e32 v95, v165
	v_readlane_b32 s1, v239, 19
	v_readlane_b32 s2, v239, 20
	v_readlane_b32 s3, v239, 21
	v_readlane_b32 s4, v239, 22
	v_readlane_b32 s5, v239, 23
	v_readlane_b32 s6, v239, 24
	v_readlane_b32 s7, v239, 25
	v_readlane_b32 s10, v239, 28
	v_readlane_b32 s11, v239, 29
	v_readlane_b32 s12, v239, 30
	v_readlane_b32 s13, v239, 31
	v_readlane_b32 s14, v239, 32
	v_readlane_b32 s15, v239, 33
	v_readlane_b32 s49, v239, 35
	v_readlane_b32 s54, v239, 40
	v_readlane_b32 s55, v239, 41
	v_readlane_b32 s56, v239, 42
	v_readlane_b32 s57, v239, 43
	v_readlane_b32 s58, v239, 44
	v_readlane_b32 s59, v239, 45
	v_readlane_b32 s60, v239, 46
	v_readlane_b32 s61, v239, 47
	v_readlane_b32 s62, v239, 48
	v_readlane_b32 s63, v239, 49
	s_branch .LBB0_84
.LBB0_83:
	v_add_u32_e32 v160, v168, v166
	v_add_u32_e32 v241, v167, v166
	v_add_u32_e32 v242, v167, v169
	v_add_u32_e32 v243, v168, v169
	ds_read_b128 v[172:175], v160 offset:16384
	ds_read_b128 v[180:183], v241
	ds_read_b128 v[214:217], v160 offset:18432
	ds_read_b128 v[218:221], v160 offset:20480
	ds_read_b128 v[222:225], v160 offset:22528
	ds_read_b128 v[244:247], v241 offset:2048
	ds_read_b128 v[248:251], v241 offset:4096
	ds_read_b128 v[252:255], v241 offset:6144
	s_add_i32 s41, s41, 64
	s_andn2_b64 vcc, exec, s[92:93]
	s_waitcnt lgkmcnt(6)
	v_mfma_f32_16x16x32_bf16 v[92:95], v[172:175], v[180:183], v[92:95]
	s_waitcnt lgkmcnt(5)
	v_mfma_f32_16x16x32_bf16 v[88:91], v[214:217], v[180:183], v[88:91]
	s_waitcnt lgkmcnt(4)
	v_mfma_f32_16x16x32_bf16 v[84:87], v[218:221], v[180:183], v[84:87]
	s_waitcnt lgkmcnt(3)
	v_mfma_f32_16x16x32_bf16 v[80:83], v[222:225], v[180:183], v[80:83]
	ds_read_b128 v[180:183], v242
	s_waitcnt lgkmcnt(3)
	v_mfma_f32_16x16x32_bf16 v[76:79], v[172:175], v[244:247], v[76:79]
	v_mfma_f32_16x16x32_bf16 v[72:75], v[214:217], v[244:247], v[72:75]
	v_mfma_f32_16x16x32_bf16 v[68:71], v[218:221], v[244:247], v[68:71]
	v_mfma_f32_16x16x32_bf16 v[64:67], v[222:225], v[244:247], v[64:67]
	ds_read_b128 v[244:247], v242 offset:2048
	s_waitcnt lgkmcnt(3)
	v_mfma_f32_16x16x32_bf16 v[60:63], v[172:175], v[248:251], v[60:63]
	s_waitcnt lgkmcnt(2)
	v_mfma_f32_16x16x32_bf16 v[44:47], v[172:175], v[252:255], v[44:47]
	ds_read_b128 v[172:175], v243 offset:16384
	v_mfma_f32_16x16x32_bf16 v[56:59], v[214:217], v[248:251], v[56:59]
	v_mfma_f32_16x16x32_bf16 v[40:43], v[214:217], v[252:255], v[40:43]
	ds_read_b128 v[214:217], v243 offset:18432
	v_mfma_f32_16x16x32_bf16 v[52:55], v[218:221], v[248:251], v[52:55]
	v_mfma_f32_16x16x32_bf16 v[36:39], v[218:221], v[252:255], v[36:39]
	ds_read_b128 v[218:221], v243 offset:20480
	v_mfma_f32_16x16x32_bf16 v[48:51], v[222:225], v[248:251], v[48:51]
	v_mfma_f32_16x16x32_bf16 v[32:35], v[222:225], v[252:255], v[32:35]
	ds_read_b128 v[222:225], v243 offset:22528
	ds_read_b128 v[248:251], v242 offset:4096
	ds_read_b128 v[252:255], v242 offset:6144
	s_waitcnt lgkmcnt(5)
	v_mfma_f32_16x16x32_bf16 v[92:95], v[172:175], v[180:183], v[92:95]
	v_mfma_f32_16x16x32_bf16 v[76:79], v[172:175], v[244:247], v[76:79]
	s_waitcnt lgkmcnt(4)
	v_mfma_f32_16x16x32_bf16 v[88:91], v[214:217], v[180:183], v[88:91]
	v_mfma_f32_16x16x32_bf16 v[72:75], v[214:217], v[244:247], v[72:75]
	s_waitcnt lgkmcnt(3)
	v_mfma_f32_16x16x32_bf16 v[84:87], v[218:221], v[180:183], v[84:87]
	v_mfma_f32_16x16x32_bf16 v[68:71], v[218:221], v[244:247], v[68:71]
	s_waitcnt lgkmcnt(2)
	v_mfma_f32_16x16x32_bf16 v[80:83], v[222:225], v[180:183], v[80:83]
	v_mfma_f32_16x16x32_bf16 v[64:67], v[222:225], v[244:247], v[64:67]
	s_waitcnt lgkmcnt(1)
	v_mfma_f32_16x16x32_bf16 v[60:63], v[172:175], v[248:251], v[60:63]
	v_mfma_f32_16x16x32_bf16 v[56:59], v[214:217], v[248:251], v[56:59]
	v_mfma_f32_16x16x32_bf16 v[52:55], v[218:221], v[248:251], v[52:55]
	v_mfma_f32_16x16x32_bf16 v[48:51], v[222:225], v[248:251], v[48:51]
	s_waitcnt lgkmcnt(0)
	s_barrier
	v_mfma_f32_16x16x32_bf16 v[44:47], v[172:175], v[252:255], v[44:47]
	v_mfma_f32_16x16x32_bf16 v[40:43], v[214:217], v[252:255], v[40:43]
	v_mfma_f32_16x16x32_bf16 v[36:39], v[218:221], v[252:255], v[36:39]
	v_mfma_f32_16x16x32_bf16 v[32:35], v[222:225], v[252:255], v[32:35]
	s_cbranch_vccz .LBB0_91
.LBB0_84:
	s_cmpk_gt_u32 s41, 0x3bf
	s_cselect_b64 s[92:93], -1, 0
	s_and_b64 vcc, exec, s[92:93]
	v_lshrrev_b32_e32 v244, 3, v184
	v_and_b32_e32 v245, 7, v184
	s_cbranch_scc1 .Lg3_last_1
	s_mov_b64 s[86:87], s[38:39]
	s_mov_b64 s[88:89], s[28:29]
	s_mov_b32 s90, 11
	s_mov_b32 s91, 0x10000
	s_add_i32 s98, s41, 64
	s_lshl_b32 s98, s98, 1
	s_branch .Lg3_load_1
.Lg3_last_1:
	s_and_b64 vcc, exec, s[22:23]
	s_cbranch_vccz .Lg3_plain_1
	s_mov_b64 s[86:87], s[34:35]
	s_mov_b64 s[88:89], s[50:51]
	s_mov_b32 s90, 10
	s_mov_b32 s91, 0x8000
	s_mov_b32 s98, 0
.Lg3_load_1:
	v_lshlrev_b32_e32 v244, s90, v244
	v_lshl_add_u32 v244, v245, 4, v244
	v_add_u32_e32 v244, s98, v244
	v_add_u32_e32 v245, s91, v244
	v_add_u32_e32 v246, s91, v245
	v_add_u32_e32 v247, s91, v246
	s_waitcnt vmcnt(7)
	ds_write_b128 v170, v[0:3]
	global_load_dwordx4 v[0:3], v244, s[86:87]
	s_waitcnt vmcnt(7)
	ds_write_b128 v170, v[4:7] offset:4096
	global_load_dwordx4 v[4:7], v245, s[86:87]
	s_waitcnt vmcnt(7)
	ds_write_b128 v170, v[8:11] offset:8192
	global_load_dwordx4 v[8:11], v246, s[86:87]
	s_waitcnt vmcnt(7)
	ds_write_b128 v170, v[12:15] offset:12288
	global_load_dwordx4 v[12:15], v247, s[86:87]
	s_waitcnt vmcnt(7)
	ds_write_b128 v170, v[16:19] offset:16384
	global_load_dwordx4 v[16:19], v244, s[88:89]
	s_waitcnt vmcnt(7)
	ds_write_b128 v170, v[20:23] offset:20480
	global_load_dwordx4 v[20:23], v245, s[88:89]
	s_waitcnt vmcnt(7)
	ds_write_b128 v170, v[24:27] offset:24576
	global_load_dwordx4 v[24:27], v246, s[88:89]
	s_waitcnt vmcnt(7)
	ds_write_b128 v170, v[28:31] offset:28672
	global_load_dwordx4 v[28:31], v247, s[88:89]
	s_branch .Lg3_done_1
.Lg3_plain_1:
	s_waitcnt vmcnt(7)
	ds_write_b128 v170, v[0:3]
	s_waitcnt vmcnt(6)
	ds_write_b128 v170, v[4:7] offset:4096
	s_waitcnt vmcnt(5)
	ds_write_b128 v170, v[8:11] offset:8192
	s_waitcnt vmcnt(4)
	ds_write_b128 v170, v[12:15] offset:12288
	s_waitcnt vmcnt(3)
	ds_write_b128 v170, v[16:19] offset:16384
	s_waitcnt vmcnt(2)
	ds_write_b128 v170, v[20:23] offset:20480
	s_waitcnt vmcnt(1)
	ds_write_b128 v170, v[24:27] offset:24576
	s_waitcnt vmcnt(0)
	ds_write_b128 v170, v[28:31] offset:28672
.Lg3_done_1:
	s_waitcnt lgkmcnt(0)
	s_barrier
	s_branch .LBB0_83
.LBB0_91:
	v_mul_f32_e32 v92, 0xbfb8aa3b, v92
	v_mul_f32_e32 v93, 0xbfb8aa3b, v93
	v_exp_f32_e32 v92, v92
	v_exp_f32_e32 v93, v93
	v_mul_f32_e32 v88, 0xbfb8aa3b, v88
	v_mul_f32_e32 v89, 0xbfb8aa3b, v89
	v_exp_f32_e32 v88, v88
	v_pk_add_f32 v[92:93], v[92:93], 1.0 op_sel_hi:[1,0]
	v_exp_f32_e32 v89, v89
	v_div_scale_f32 v160, s[28:29], v93, v93, 1.0
	v_rcp_f32_e32 v161, v160
	v_pk_add_f32 v[88:89], v[88:89], 1.0 op_sel_hi:[1,0]
	v_mul_f32_e32 v84, 0xbfb8aa3b, v84
	v_mul_f32_e32 v85, 0xbfb8aa3b, v85
	v_fma_f32 v166, -v160, v161, 1.0
	v_fmac_f32_e32 v161, v166, v161
	v_div_scale_f32 v166, vcc, 1.0, v93, 1.0
	v_mul_f32_e32 v167, v166, v161
	v_fma_f32 v168, -v160, v167, v166
	v_fmac_f32_e32 v167, v168, v161
	v_fma_f32 v160, -v160, v167, v166
	v_div_fmas_f32 v160, v160, v161, v167
	v_div_fixup_f32 v93, v160, v93, 1.0
	v_div_scale_f32 v160, s[28:29], v92, v92, 1.0
	v_rcp_f32_e32 v161, v160
	v_exp_f32_e32 v84, v84
	v_exp_f32_e32 v85, v85
	v_mul_f32_e32 v80, 0xbfb8aa3b, v80
	v_fma_f32 v166, -v160, v161, 1.0
	v_fmac_f32_e32 v161, v166, v161
	v_div_scale_f32 v166, vcc, 1.0, v92, 1.0
	v_mul_f32_e32 v167, v166, v161
	v_fma_f32 v168, -v160, v167, v166
	v_fmac_f32_e32 v167, v168, v161
	v_fma_f32 v160, -v160, v167, v166
	v_div_fmas_f32 v160, v160, v161, v167
	v_div_fixup_f32 v92, v160, v92, 1.0
	v_cvt_pk_bf16_f32 v160, v92, v93
	v_mul_f32_e32 v92, 0xbfb8aa3b, v94
	v_mul_f32_e32 v93, 0xbfb8aa3b, v95
	v_exp_f32_e32 v92, v92
	v_exp_f32_e32 v93, v93
	v_pk_add_f32 v[84:85], v[84:85], 1.0 op_sel_hi:[1,0]
	v_mul_f32_e32 v81, 0xbfb8aa3b, v81
	v_exp_f32_e32 v80, v80
	v_pk_add_f32 v[92:93], v[92:93], 1.0 op_sel_hi:[1,0]
	v_exp_f32_e32 v81, v81
	v_div_scale_f32 v94, s[28:29], v93, v93, 1.0
	v_rcp_f32_e32 v95, v94
	v_pk_add_f32 v[80:81], v[80:81], 1.0 op_sel_hi:[1,0]
	v_mul_f32_e32 v76, 0xbfb8aa3b, v76
	v_mul_f32_e32 v77, 0xbfb8aa3b, v77
	v_fma_f32 v161, -v94, v95, 1.0
	v_fmac_f32_e32 v95, v161, v95
	v_div_scale_f32 v161, vcc, 1.0, v93, 1.0
	v_mul_f32_e32 v166, v161, v95
	v_fma_f32 v167, -v94, v166, v161
	v_fmac_f32_e32 v166, v167, v95
	v_fma_f32 v94, -v94, v166, v161
	v_div_fmas_f32 v94, v94, v95, v166
	v_div_fixup_f32 v93, v94, v93, 1.0
	v_div_scale_f32 v94, s[28:29], v92, v92, 1.0
	v_rcp_f32_e32 v95, v94
	v_exp_f32_e32 v76, v76
	v_exp_f32_e32 v77, v77
	v_mul_f32_e32 v72, 0xbfb8aa3b, v72
	v_fma_f32 v161, -v94, v95, 1.0
	v_fmac_f32_e32 v95, v161, v95
	v_div_scale_f32 v161, vcc, 1.0, v92, 1.0
	v_mul_f32_e32 v166, v161, v95
	v_fma_f32 v167, -v94, v166, v161
	v_fmac_f32_e32 v166, v167, v95
	v_fma_f32 v94, -v94, v166, v161
	v_div_fmas_f32 v94, v94, v95, v166
	v_div_fixup_f32 v92, v94, v92, 1.0
	v_cvt_pk_bf16_f32 v92, v92, v93
	ds_write2st64_b32 v162, v160, v92 offset0:128 offset1:132
	v_div_scale_f32 v92, s[28:29], v89, v89, 1.0
	v_rcp_f32_e32 v93, v92
	v_pk_add_f32 v[76:77], v[76:77], 1.0 op_sel_hi:[1,0]
	v_mul_f32_e32 v73, 0xbfb8aa3b, v73
	v_exp_f32_e32 v72, v72
	v_fma_f32 v94, -v92, v93, 1.0
	v_fmac_f32_e32 v93, v94, v93
	v_div_scale_f32 v94, vcc, 1.0, v89, 1.0
	v_mul_f32_e32 v95, v94, v93
	v_fma_f32 v160, -v92, v95, v94
	v_fmac_f32_e32 v95, v160, v93
	v_fma_f32 v92, -v92, v95, v94
	v_div_fmas_f32 v92, v92, v93, v95
	v_div_fixup_f32 v89, v92, v89, 1.0
	v_div_scale_f32 v92, s[28:29], v88, v88, 1.0
	v_rcp_f32_e32 v93, v92
	v_exp_f32_e32 v73, v73
	v_mul_f32_e32 v68, 0xbfb8aa3b, v68
	v_mul_f32_e32 v69, 0xbfb8aa3b, v69
	v_fma_f32 v94, -v92, v93, 1.0
	v_fmac_f32_e32 v93, v94, v93
	v_div_scale_f32 v94, vcc, 1.0, v88, 1.0
	v_mul_f32_e32 v95, v94, v93
	v_fma_f32 v160, -v92, v95, v94
	v_fmac_f32_e32 v95, v160, v93
	v_fma_f32 v92, -v92, v95, v94
	v_div_fmas_f32 v92, v92, v93, v95
	v_div_fixup_f32 v88, v92, v88, 1.0
	v_cvt_pk_bf16_f32 v92, v88, v89
	v_mul_f32_e32 v88, 0xbfb8aa3b, v90
	v_mul_f32_e32 v89, 0xbfb8aa3b, v91
	v_exp_f32_e32 v88, v88
	v_exp_f32_e32 v89, v89
	v_pk_add_f32 v[72:73], v[72:73], 1.0 op_sel_hi:[1,0]
	v_exp_f32_e32 v68, v68
	v_exp_f32_e32 v69, v69
	v_pk_add_f32 v[88:89], v[88:89], 1.0 op_sel_hi:[1,0]
	v_mul_f32_e32 v64, 0xbfb8aa3b, v64
	v_div_scale_f32 v90, s[28:29], v89, v89, 1.0
	v_rcp_f32_e32 v91, v90
	v_pk_add_f32 v[68:69], v[68:69], 1.0 op_sel_hi:[1,0]
	v_mul_f32_e32 v65, 0xbfb8aa3b, v65
	v_exp_f32_e32 v64, v64
	v_fma_f32 v93, -v90, v91, 1.0
	v_fmac_f32_e32 v91, v93, v91
	v_div_scale_f32 v93, vcc, 1.0, v89, 1.0
	v_mul_f32_e32 v94, v93, v91
	v_fma_f32 v95, -v90, v94, v93
	v_fmac_f32_e32 v94, v95, v91
	v_fma_f32 v90, -v90, v94, v93
	v_div_fmas_f32 v90, v90, v91, v94
	v_div_fixup_f32 v89, v90, v89, 1.0
	v_div_scale_f32 v90, s[28:29], v88, v88, 1.0
	v_rcp_f32_e32 v91, v90
	v_exp_f32_e32 v65, v65
	v_mul_f32_e32 v60, 0xbfb8aa3b, v60
	v_mul_f32_e32 v61, 0xbfb8aa3b, v61
	v_fma_f32 v93, -v90, v91, 1.0
	v_fmac_f32_e32 v91, v93, v91
	v_div_scale_f32 v93, vcc, 1.0, v88, 1.0
	v_mul_f32_e32 v94, v93, v91
	v_fma_f32 v95, -v90, v94, v93
	v_fmac_f32_e32 v94, v95, v91
	v_fma_f32 v90, -v90, v94, v93
	v_div_fmas_f32 v90, v90, v91, v94
	v_div_fixup_f32 v88, v90, v88, 1.0
	v_cvt_pk_bf16_f32 v88, v88, v89
	ds_write2st64_b32 v162, v92, v88 offset0:136 offset1:140
	v_div_scale_f32 v88, s[28:29], v85, v85, 1.0
	v_rcp_f32_e32 v89, v88
	v_pk_add_f32 v[64:65], v[64:65], 1.0 op_sel_hi:[1,0]
	v_exp_f32_e32 v60, v60
	v_exp_f32_e32 v61, v61
	v_fma_f32 v90, -v88, v89, 1.0
	v_fmac_f32_e32 v89, v90, v89
	v_div_scale_f32 v90, vcc, 1.0, v85, 1.0
	v_mul_f32_e32 v91, v90, v89
	v_fma_f32 v92, -v88, v91, v90
	v_fmac_f32_e32 v91, v92, v89
	v_fma_f32 v88, -v88, v91, v90
	v_div_fmas_f32 v88, v88, v89, v91
	v_div_fixup_f32 v85, v88, v85, 1.0
	v_div_scale_f32 v88, s[28:29], v84, v84, 1.0
	v_rcp_f32_e32 v89, v88
	v_pk_add_f32 v[60:61], v[60:61], 1.0 op_sel_hi:[1,0]
	v_mul_f32_e32 v56, 0xbfb8aa3b, v56
	v_mul_f32_e32 v57, 0xbfb8aa3b, v57
	v_fma_f32 v90, -v88, v89, 1.0
	v_fmac_f32_e32 v89, v90, v89
	v_div_scale_f32 v90, vcc, 1.0, v84, 1.0
	v_mul_f32_e32 v91, v90, v89
	v_fma_f32 v92, -v88, v91, v90
	v_fmac_f32_e32 v91, v92, v89
	v_fma_f32 v88, -v88, v91, v90
	v_div_fmas_f32 v88, v88, v89, v91
	v_div_fixup_f32 v84, v88, v84, 1.0
	v_cvt_pk_bf16_f32 v88, v84, v85
	v_mul_f32_e32 v84, 0xbfb8aa3b, v86
	v_mul_f32_e32 v85, 0xbfb8aa3b, v87
	v_exp_f32_e32 v84, v84
	v_exp_f32_e32 v85, v85
	v_exp_f32_e32 v56, v56
	v_exp_f32_e32 v57, v57
	v_mul_f32_e32 v52, 0xbfb8aa3b, v52
	v_pk_add_f32 v[84:85], v[84:85], 1.0 op_sel_hi:[1,0]
	v_mul_f32_e32 v53, 0xbfb8aa3b, v53
	v_div_scale_f32 v86, s[28:29], v85, v85, 1.0
	v_rcp_f32_e32 v87, v86
	v_pk_add_f32 v[56:57], v[56:57], 1.0 op_sel_hi:[1,0]
	v_exp_f32_e32 v52, v52
	v_exp_f32_e32 v53, v53
	v_fma_f32 v89, -v86, v87, 1.0
	v_fmac_f32_e32 v87, v89, v87
	v_div_scale_f32 v89, vcc, 1.0, v85, 1.0
	v_mul_f32_e32 v90, v89, v87
	v_fma_f32 v91, -v86, v90, v89
	v_fmac_f32_e32 v90, v91, v87
	v_fma_f32 v86, -v86, v90, v89
	v_div_fmas_f32 v86, v86, v87, v90
	v_div_fixup_f32 v85, v86, v85, 1.0
	v_div_scale_f32 v86, s[28:29], v84, v84, 1.0
	v_rcp_f32_e32 v87, v86
	v_pk_add_f32 v[52:53], v[52:53], 1.0 op_sel_hi:[1,0]
	v_mul_f32_e32 v48, 0xbfb8aa3b, v48
	v_mul_f32_e32 v49, 0xbfb8aa3b, v49
	v_fma_f32 v89, -v86, v87, 1.0
	v_fmac_f32_e32 v87, v89, v87
	v_div_scale_f32 v89, vcc, 1.0, v84, 1.0
	v_mul_f32_e32 v90, v89, v87
	v_fma_f32 v91, -v86, v90, v89
	v_fmac_f32_e32 v90, v91, v87
	v_fma_f32 v86, -v86, v90, v89
	v_div_fmas_f32 v86, v86, v87, v90
	v_div_fixup_f32 v84, v86, v84, 1.0
	v_cvt_pk_bf16_f32 v84, v84, v85
	ds_write2st64_b32 v162, v88, v84 offset0:144 offset1:148
	v_div_scale_f32 v84, s[28:29], v81, v81, 1.0
	v_rcp_f32_e32 v85, v84
	v_exp_f32_e32 v48, v48
	v_exp_f32_e32 v49, v49
	v_mul_f32_e32 v44, 0xbfb8aa3b, v44
	v_fma_f32 v86, -v84, v85, 1.0
	v_fmac_f32_e32 v85, v86, v85
	v_div_scale_f32 v86, vcc, 1.0, v81, 1.0
	v_mul_f32_e32 v87, v86, v85
	v_fma_f32 v88, -v84, v87, v86
	v_fmac_f32_e32 v87, v88, v85
	v_fma_f32 v84, -v84, v87, v86
	v_div_fmas_f32 v84, v84, v85, v87
	v_div_fixup_f32 v81, v84, v81, 1.0
	v_div_scale_f32 v84, s[28:29], v80, v80, 1.0
	v_rcp_f32_e32 v85, v84
	v_pk_add_f32 v[48:49], v[48:49], 1.0 op_sel_hi:[1,0]
	v_mul_f32_e32 v45, 0xbfb8aa3b, v45
	v_exp_f32_e32 v44, v44
	v_fma_f32 v86, -v84, v85, 1.0
	v_fmac_f32_e32 v85, v86, v85
	v_div_scale_f32 v86, vcc, 1.0, v80, 1.0
	v_mul_f32_e32 v87, v86, v85
	v_fma_f32 v88, -v84, v87, v86
	v_fmac_f32_e32 v87, v88, v85
	v_fma_f32 v84, -v84, v87, v86
	v_div_fmas_f32 v84, v84, v85, v87
	v_div_fixup_f32 v80, v84, v80, 1.0
	v_cvt_pk_bf16_f32 v84, v80, v81
	v_mul_f32_e32 v80, 0xbfb8aa3b, v82
	v_mul_f32_e32 v81, 0xbfb8aa3b, v83
	v_exp_f32_e32 v80, v80
	v_exp_f32_e32 v81, v81
	v_exp_f32_e32 v45, v45
	v_mul_f32_e32 v40, 0xbfb8aa3b, v40
	v_mul_f32_e32 v41, 0xbfb8aa3b, v41
	v_pk_add_f32 v[80:81], v[80:81], 1.0 op_sel_hi:[1,0]
	v_pk_add_f32 v[44:45], v[44:45], 1.0 op_sel_hi:[1,0]
	v_div_scale_f32 v82, s[28:29], v81, v81, 1.0
	v_rcp_f32_e32 v83, v82
	v_exp_f32_e32 v40, v40
	v_exp_f32_e32 v41, v41
	v_mul_f32_e32 v36, 0xbfb8aa3b, v36
	v_fma_f32 v85, -v82, v83, 1.0
	v_fmac_f32_e32 v83, v85, v83
	v_div_scale_f32 v85, vcc, 1.0, v81, 1.0
	v_mul_f32_e32 v86, v85, v83
	v_fma_f32 v87, -v82, v86, v85
	v_fmac_f32_e32 v86, v87, v83
	v_fma_f32 v82, -v82, v86, v85
	v_div_fmas_f32 v82, v82, v83, v86
	v_div_fixup_f32 v81, v82, v81, 1.0
	v_div_scale_f32 v82, s[28:29], v80, v80, 1.0
	v_rcp_f32_e32 v83, v82
	v_pk_add_f32 v[40:41], v[40:41], 1.0 op_sel_hi:[1,0]
	v_mul_f32_e32 v37, 0xbfb8aa3b, v37
	v_exp_f32_e32 v36, v36
	v_fma_f32 v85, -v82, v83, 1.0
	v_fmac_f32_e32 v83, v85, v83
	v_div_scale_f32 v85, vcc, 1.0, v80, 1.0
	v_mul_f32_e32 v86, v85, v83
	v_fma_f32 v87, -v82, v86, v85
	v_fmac_f32_e32 v86, v87, v83
	v_fma_f32 v82, -v82, v86, v85
	v_div_fmas_f32 v82, v82, v83, v86
	v_div_fixup_f32 v80, v82, v80, 1.0
	v_cvt_pk_bf16_f32 v80, v80, v81
	ds_write2st64_b32 v162, v84, v80 offset0:152 offset1:156
	v_div_scale_f32 v80, s[28:29], v77, v77, 1.0
	v_rcp_f32_e32 v81, v80
	v_exp_f32_e32 v37, v37
	v_mul_f32_e32 v32, 0xbfb8aa3b, v32
	v_mul_f32_e32 v33, 0xbfb8aa3b, v33
	v_fma_f32 v82, -v80, v81, 1.0
	v_fmac_f32_e32 v81, v82, v81
	v_div_scale_f32 v82, vcc, 1.0, v77, 1.0
	v_mul_f32_e32 v83, v82, v81
	v_fma_f32 v84, -v80, v83, v82
	v_fmac_f32_e32 v83, v84, v81
	v_fma_f32 v80, -v80, v83, v82
	v_div_fmas_f32 v80, v80, v81, v83
	v_div_fixup_f32 v77, v80, v77, 1.0
	v_div_scale_f32 v80, s[28:29], v76, v76, 1.0
	v_rcp_f32_e32 v81, v80
	v_pk_add_f32 v[36:37], v[36:37], 1.0 op_sel_hi:[1,0]
	v_exp_f32_e32 v32, v32
	v_exp_f32_e32 v33, v33
	v_fma_f32 v82, -v80, v81, 1.0
	v_fmac_f32_e32 v81, v82, v81
	v_div_scale_f32 v82, vcc, 1.0, v76, 1.0
	v_mul_f32_e32 v83, v82, v81
	v_fma_f32 v84, -v80, v83, v82
	v_fmac_f32_e32 v83, v84, v81
	v_fma_f32 v80, -v80, v83, v82
	v_div_fmas_f32 v80, v80, v81, v83
	v_div_fixup_f32 v76, v80, v76, 1.0
	v_cvt_pk_bf16_f32 v80, v76, v77
	v_mul_f32_e32 v76, 0xbfb8aa3b, v78
	v_mul_f32_e32 v77, 0xbfb8aa3b, v79
	v_exp_f32_e32 v76, v76
	v_exp_f32_e32 v77, v77
	v_pk_add_f32 v[32:33], v[32:33], 1.0 op_sel_hi:[1,0]
	s_cmp_eq_u32 s40, 3
	s_mov_b64 s[92:93], s[42:43]
	v_pk_add_f32 v[76:77], v[76:77], 1.0 op_sel_hi:[1,0]
	s_nop 0
	v_div_scale_f32 v78, s[28:29], v77, v77, 1.0
	v_rcp_f32_e32 v79, v78
	s_nop 0
	v_fma_f32 v81, -v78, v79, 1.0
	v_fmac_f32_e32 v79, v81, v79
	v_div_scale_f32 v81, vcc, 1.0, v77, 1.0
	v_mul_f32_e32 v82, v81, v79
	v_fma_f32 v83, -v78, v82, v81
	v_fmac_f32_e32 v82, v83, v79
	v_fma_f32 v78, -v78, v82, v81
	v_div_fmas_f32 v78, v78, v79, v82
	v_div_fixup_f32 v77, v78, v77, 1.0
	v_div_scale_f32 v78, s[28:29], v76, v76, 1.0
	v_rcp_f32_e32 v79, v78
	s_nop 0
	v_fma_f32 v81, -v78, v79, 1.0
	v_fmac_f32_e32 v79, v81, v79
	v_div_scale_f32 v81, vcc, 1.0, v76, 1.0
	v_mul_f32_e32 v82, v81, v79
	v_fma_f32 v83, -v78, v82, v81
	v_fmac_f32_e32 v82, v83, v79
	v_fma_f32 v78, -v78, v82, v81
	v_div_fmas_f32 v78, v78, v79, v82
	v_div_fixup_f32 v76, v78, v76, 1.0
	v_cvt_pk_bf16_f32 v76, v76, v77
	ds_write2st64_b32 v162, v80, v76 offset0:160 offset1:164
	v_div_scale_f32 v76, s[28:29], v73, v73, 1.0
	v_rcp_f32_e32 v77, v76
	s_nop 0
	v_fma_f32 v78, -v76, v77, 1.0
	v_fmac_f32_e32 v77, v78, v77
	v_div_scale_f32 v78, vcc, 1.0, v73, 1.0
	v_mul_f32_e32 v79, v78, v77
	v_fma_f32 v80, -v76, v79, v78
	v_fmac_f32_e32 v79, v80, v77
	v_fma_f32 v76, -v76, v79, v78
	v_div_fmas_f32 v76, v76, v77, v79
	v_div_fixup_f32 v73, v76, v73, 1.0
	v_div_scale_f32 v76, s[28:29], v72, v72, 1.0
	v_rcp_f32_e32 v77, v76
	s_nop 0
	v_fma_f32 v78, -v76, v77, 1.0
	v_fmac_f32_e32 v77, v78, v77
	v_div_scale_f32 v78, vcc, 1.0, v72, 1.0
	v_mul_f32_e32 v79, v78, v77
	v_fma_f32 v80, -v76, v79, v78
	v_fmac_f32_e32 v79, v80, v77
	v_fma_f32 v76, -v76, v79, v78
	v_div_fmas_f32 v76, v76, v77, v79
	v_div_fixup_f32 v72, v76, v72, 1.0
	v_cvt_pk_bf16_f32 v76, v72, v73
	v_mul_f32_e32 v72, 0xbfb8aa3b, v74
	v_mul_f32_e32 v73, 0xbfb8aa3b, v75
	v_exp_f32_e32 v72, v72
	v_exp_f32_e32 v73, v73
	s_nop 0
	v_pk_add_f32 v[72:73], v[72:73], 1.0 op_sel_hi:[1,0]
	s_nop 0
	v_div_scale_f32 v74, s[28:29], v73, v73, 1.0
	v_rcp_f32_e32 v75, v74
	s_nop 0
	v_fma_f32 v77, -v74, v75, 1.0
	v_fmac_f32_e32 v75, v77, v75
	v_div_scale_f32 v77, vcc, 1.0, v73, 1.0
	v_mul_f32_e32 v78, v77, v75
	v_fma_f32 v79, -v74, v78, v77
	v_fmac_f32_e32 v78, v79, v75
	v_fma_f32 v74, -v74, v78, v77
	v_div_fmas_f32 v74, v74, v75, v78
	v_div_fixup_f32 v73, v74, v73, 1.0
	v_div_scale_f32 v74, s[28:29], v72, v72, 1.0
	v_rcp_f32_e32 v75, v74
	s_nop 0
	v_fma_f32 v77, -v74, v75, 1.0
	v_fmac_f32_e32 v75, v77, v75
	v_div_scale_f32 v77, vcc, 1.0, v72, 1.0
	v_mul_f32_e32 v78, v77, v75
	v_fma_f32 v79, -v74, v78, v77
	v_fmac_f32_e32 v78, v79, v75
	v_fma_f32 v74, -v74, v78, v77
	v_div_fmas_f32 v74, v74, v75, v78
	v_div_fixup_f32 v72, v74, v72, 1.0
	v_cvt_pk_bf16_f32 v72, v72, v73
	ds_write2st64_b32 v162, v76, v72 offset0:168 offset1:172
	v_div_scale_f32 v72, s[28:29], v69, v69, 1.0
	v_rcp_f32_e32 v73, v72
	s_nop 0
	v_fma_f32 v74, -v72, v73, 1.0
	v_fmac_f32_e32 v73, v74, v73
	v_div_scale_f32 v74, vcc, 1.0, v69, 1.0
	v_mul_f32_e32 v75, v74, v73
	v_fma_f32 v76, -v72, v75, v74
	v_fmac_f32_e32 v75, v76, v73
	v_fma_f32 v72, -v72, v75, v74
	v_div_fmas_f32 v72, v72, v73, v75
	v_div_fixup_f32 v69, v72, v69, 1.0
	v_div_scale_f32 v72, s[28:29], v68, v68, 1.0
	v_rcp_f32_e32 v73, v72
	s_nop 0
	v_fma_f32 v74, -v72, v73, 1.0
	v_fmac_f32_e32 v73, v74, v73
	v_div_scale_f32 v74, vcc, 1.0, v68, 1.0
	v_mul_f32_e32 v75, v74, v73
	v_fma_f32 v76, -v72, v75, v74
	v_fmac_f32_e32 v75, v76, v73
	v_fma_f32 v72, -v72, v75, v74
	v_div_fmas_f32 v72, v72, v73, v75
	v_div_fixup_f32 v68, v72, v68, 1.0
	v_cvt_pk_bf16_f32 v72, v68, v69
	v_mul_f32_e32 v68, 0xbfb8aa3b, v70
	v_mul_f32_e32 v69, 0xbfb8aa3b, v71
	v_exp_f32_e32 v68, v68
	v_exp_f32_e32 v69, v69
	s_nop 0
	v_pk_add_f32 v[68:69], v[68:69], 1.0 op_sel_hi:[1,0]
	s_nop 0
	v_div_scale_f32 v70, s[28:29], v69, v69, 1.0
	v_rcp_f32_e32 v71, v70
	s_nop 0
	v_fma_f32 v73, -v70, v71, 1.0
	v_fmac_f32_e32 v71, v73, v71
	v_div_scale_f32 v73, vcc, 1.0, v69, 1.0
	v_mul_f32_e32 v74, v73, v71
	v_fma_f32 v75, -v70, v74, v73
	v_fmac_f32_e32 v74, v75, v71
	v_fma_f32 v70, -v70, v74, v73
	v_div_fmas_f32 v70, v70, v71, v74
	v_div_fixup_f32 v69, v70, v69, 1.0
	v_div_scale_f32 v70, s[28:29], v68, v68, 1.0
	v_rcp_f32_e32 v71, v70
	s_nop 0
	v_fma_f32 v73, -v70, v71, 1.0
	v_fmac_f32_e32 v71, v73, v71
	v_div_scale_f32 v73, vcc, 1.0, v68, 1.0
	v_mul_f32_e32 v74, v73, v71
	v_fma_f32 v75, -v70, v74, v73
	v_fmac_f32_e32 v74, v75, v71
	v_fma_f32 v70, -v70, v74, v73
	v_div_fmas_f32 v70, v70, v71, v74
	v_div_fixup_f32 v68, v70, v68, 1.0
	v_cvt_pk_bf16_f32 v68, v68, v69
	ds_write2st64_b32 v162, v72, v68 offset0:176 offset1:180
	v_div_scale_f32 v68, s[28:29], v65, v65, 1.0
	v_rcp_f32_e32 v69, v68
	s_nop 0
	v_fma_f32 v70, -v68, v69, 1.0
	v_fmac_f32_e32 v69, v70, v69
	v_div_scale_f32 v70, vcc, 1.0, v65, 1.0
	v_mul_f32_e32 v71, v70, v69
	v_fma_f32 v72, -v68, v71, v70
	v_fmac_f32_e32 v71, v72, v69
	v_fma_f32 v68, -v68, v71, v70
	v_div_fmas_f32 v68, v68, v69, v71
	v_div_fixup_f32 v65, v68, v65, 1.0
	v_div_scale_f32 v68, s[28:29], v64, v64, 1.0
	v_rcp_f32_e32 v69, v68
	s_nop 0
	v_fma_f32 v70, -v68, v69, 1.0
	v_fmac_f32_e32 v69, v70, v69
	v_div_scale_f32 v70, vcc, 1.0, v64, 1.0
	v_mul_f32_e32 v71, v70, v69
	v_fma_f32 v72, -v68, v71, v70
	v_fmac_f32_e32 v71, v72, v69
	v_fma_f32 v68, -v68, v71, v70
	v_div_fmas_f32 v68, v68, v69, v71
	v_div_fixup_f32 v64, v68, v64, 1.0
	v_cvt_pk_bf16_f32 v68, v64, v65
	v_mul_f32_e32 v64, 0xbfb8aa3b, v66
	v_mul_f32_e32 v65, 0xbfb8aa3b, v67
	v_exp_f32_e32 v64, v64
	v_exp_f32_e32 v65, v65
	s_nop 0
	v_pk_add_f32 v[64:65], v[64:65], 1.0 op_sel_hi:[1,0]
	s_nop 0
	v_div_scale_f32 v66, s[28:29], v65, v65, 1.0
	v_rcp_f32_e32 v67, v66
	s_nop 0
	v_fma_f32 v69, -v66, v67, 1.0
	v_fmac_f32_e32 v67, v69, v67
	v_div_scale_f32 v69, vcc, 1.0, v65, 1.0
	v_mul_f32_e32 v70, v69, v67
	v_fma_f32 v71, -v66, v70, v69
	v_fmac_f32_e32 v70, v71, v67
	v_fma_f32 v66, -v66, v70, v69
	v_div_fmas_f32 v66, v66, v67, v70
	v_div_fixup_f32 v65, v66, v65, 1.0
	v_div_scale_f32 v66, s[28:29], v64, v64, 1.0
	v_rcp_f32_e32 v67, v66
	s_nop 0
	v_fma_f32 v69, -v66, v67, 1.0
	v_fmac_f32_e32 v67, v69, v67
	v_div_scale_f32 v69, vcc, 1.0, v64, 1.0
	v_mul_f32_e32 v70, v69, v67
	v_fma_f32 v71, -v66, v70, v69
	v_fmac_f32_e32 v70, v71, v67
	v_fma_f32 v66, -v66, v70, v69
	v_div_fmas_f32 v66, v66, v67, v70
	v_div_fixup_f32 v64, v66, v64, 1.0
	v_cvt_pk_bf16_f32 v64, v64, v65
	ds_write2st64_b32 v162, v68, v64 offset0:184 offset1:188
	v_div_scale_f32 v64, s[28:29], v61, v61, 1.0
	v_rcp_f32_e32 v65, v64
	s_nop 0
	v_fma_f32 v66, -v64, v65, 1.0
	v_fmac_f32_e32 v65, v66, v65
	v_div_scale_f32 v66, vcc, 1.0, v61, 1.0
	v_mul_f32_e32 v67, v66, v65
	v_fma_f32 v68, -v64, v67, v66
	v_fmac_f32_e32 v67, v68, v65
	v_fma_f32 v64, -v64, v67, v66
	v_div_fmas_f32 v64, v64, v65, v67
	v_div_fixup_f32 v61, v64, v61, 1.0
	v_div_scale_f32 v64, s[28:29], v60, v60, 1.0
	v_rcp_f32_e32 v65, v64
	s_nop 0
	v_fma_f32 v66, -v64, v65, 1.0
	v_fmac_f32_e32 v65, v66, v65
	v_div_scale_f32 v66, vcc, 1.0, v60, 1.0
	v_mul_f32_e32 v67, v66, v65
	v_fma_f32 v68, -v64, v67, v66
	v_fmac_f32_e32 v67, v68, v65
	v_fma_f32 v64, -v64, v67, v66
	v_div_fmas_f32 v64, v64, v65, v67
	v_div_fixup_f32 v60, v64, v60, 1.0
	v_cvt_pk_bf16_f32 v64, v60, v61
	v_mul_f32_e32 v60, 0xbfb8aa3b, v62
	v_mul_f32_e32 v61, 0xbfb8aa3b, v63
	v_exp_f32_e32 v60, v60
	v_exp_f32_e32 v61, v61
	s_nop 0
	v_pk_add_f32 v[60:61], v[60:61], 1.0 op_sel_hi:[1,0]
	s_nop 0
	v_div_scale_f32 v62, s[28:29], v61, v61, 1.0
	v_rcp_f32_e32 v63, v62
	s_nop 0
	v_fma_f32 v65, -v62, v63, 1.0
	v_fmac_f32_e32 v63, v65, v63
	v_div_scale_f32 v65, vcc, 1.0, v61, 1.0
	v_mul_f32_e32 v66, v65, v63
	v_fma_f32 v67, -v62, v66, v65
	v_fmac_f32_e32 v66, v67, v63
	v_fma_f32 v62, -v62, v66, v65
	v_div_fmas_f32 v62, v62, v63, v66
	v_div_fixup_f32 v61, v62, v61, 1.0
	v_div_scale_f32 v62, s[28:29], v60, v60, 1.0
	v_rcp_f32_e32 v63, v62
	s_nop 0
	v_fma_f32 v65, -v62, v63, 1.0
	v_fmac_f32_e32 v63, v65, v63
	v_div_scale_f32 v65, vcc, 1.0, v60, 1.0
	v_mul_f32_e32 v66, v65, v63
	v_fma_f32 v67, -v62, v66, v65
	v_fmac_f32_e32 v66, v67, v63
	v_fma_f32 v62, -v62, v66, v65
	v_div_fmas_f32 v62, v62, v63, v66
	v_div_fixup_f32 v60, v62, v60, 1.0
	v_cvt_pk_bf16_f32 v60, v60, v61
	ds_write2st64_b32 v162, v64, v60 offset0:192 offset1:196
	v_div_scale_f32 v60, s[28:29], v57, v57, 1.0
	v_rcp_f32_e32 v61, v60
	s_nop 0
	v_fma_f32 v62, -v60, v61, 1.0
	v_fmac_f32_e32 v61, v62, v61
	v_div_scale_f32 v62, vcc, 1.0, v57, 1.0
	v_mul_f32_e32 v63, v62, v61
	v_fma_f32 v64, -v60, v63, v62
	v_fmac_f32_e32 v63, v64, v61
	v_fma_f32 v60, -v60, v63, v62
	v_div_fmas_f32 v60, v60, v61, v63
	v_div_fixup_f32 v57, v60, v57, 1.0
	v_div_scale_f32 v60, s[28:29], v56, v56, 1.0
	v_rcp_f32_e32 v61, v60
	s_nop 0
	v_fma_f32 v62, -v60, v61, 1.0
	v_fmac_f32_e32 v61, v62, v61
	v_div_scale_f32 v62, vcc, 1.0, v56, 1.0
	v_mul_f32_e32 v63, v62, v61
	v_fma_f32 v64, -v60, v63, v62
	v_fmac_f32_e32 v63, v64, v61
	v_fma_f32 v60, -v60, v63, v62
	v_div_fmas_f32 v60, v60, v61, v63
	v_div_fixup_f32 v56, v60, v56, 1.0
	v_cvt_pk_bf16_f32 v60, v56, v57
	v_mul_f32_e32 v56, 0xbfb8aa3b, v58
	v_mul_f32_e32 v57, 0xbfb8aa3b, v59
	v_exp_f32_e32 v56, v56
	v_exp_f32_e32 v57, v57
	s_nop 0
	v_pk_add_f32 v[56:57], v[56:57], 1.0 op_sel_hi:[1,0]
	s_nop 0
	v_div_scale_f32 v58, s[28:29], v57, v57, 1.0
	v_rcp_f32_e32 v59, v58
	s_nop 0
	v_fma_f32 v61, -v58, v59, 1.0
	v_fmac_f32_e32 v59, v61, v59
	v_div_scale_f32 v61, vcc, 1.0, v57, 1.0
	v_mul_f32_e32 v62, v61, v59
	v_fma_f32 v63, -v58, v62, v61
	v_fmac_f32_e32 v62, v63, v59
	v_fma_f32 v58, -v58, v62, v61
	v_div_fmas_f32 v58, v58, v59, v62
	v_div_fixup_f32 v57, v58, v57, 1.0
	v_div_scale_f32 v58, s[28:29], v56, v56, 1.0
	v_rcp_f32_e32 v59, v58
	s_nop 0
	v_fma_f32 v61, -v58, v59, 1.0
	v_fmac_f32_e32 v59, v61, v59
	v_div_scale_f32 v61, vcc, 1.0, v56, 1.0
	v_mul_f32_e32 v62, v61, v59
	v_fma_f32 v63, -v58, v62, v61
	v_fmac_f32_e32 v62, v63, v59
	v_fma_f32 v58, -v58, v62, v61
	v_div_fmas_f32 v58, v58, v59, v62
	v_div_fixup_f32 v56, v58, v56, 1.0
	v_cvt_pk_bf16_f32 v56, v56, v57
	ds_write2st64_b32 v162, v60, v56 offset0:200 offset1:204
	v_div_scale_f32 v56, s[28:29], v53, v53, 1.0
	v_rcp_f32_e32 v57, v56
	s_nop 0
	v_fma_f32 v58, -v56, v57, 1.0
	v_fmac_f32_e32 v57, v58, v57
	v_div_scale_f32 v58, vcc, 1.0, v53, 1.0
	v_mul_f32_e32 v59, v58, v57
	v_fma_f32 v60, -v56, v59, v58
	v_fmac_f32_e32 v59, v60, v57
	v_fma_f32 v56, -v56, v59, v58
	v_div_fmas_f32 v56, v56, v57, v59
	v_div_fixup_f32 v53, v56, v53, 1.0
	v_div_scale_f32 v56, s[28:29], v52, v52, 1.0
	v_rcp_f32_e32 v57, v56
	s_nop 0
	v_fma_f32 v58, -v56, v57, 1.0
	v_fmac_f32_e32 v57, v58, v57
	v_div_scale_f32 v58, vcc, 1.0, v52, 1.0
	v_mul_f32_e32 v59, v58, v57
	v_fma_f32 v60, -v56, v59, v58
	v_fmac_f32_e32 v59, v60, v57
	v_fma_f32 v56, -v56, v59, v58
	v_div_fmas_f32 v56, v56, v57, v59
	v_div_fixup_f32 v52, v56, v52, 1.0
	v_cvt_pk_bf16_f32 v56, v52, v53
	v_mul_f32_e32 v52, 0xbfb8aa3b, v54
	v_mul_f32_e32 v53, 0xbfb8aa3b, v55
	v_exp_f32_e32 v52, v52
	v_exp_f32_e32 v53, v53
	s_nop 0
	v_pk_add_f32 v[52:53], v[52:53], 1.0 op_sel_hi:[1,0]
	s_nop 0
	v_div_scale_f32 v54, s[28:29], v53, v53, 1.0
	v_rcp_f32_e32 v55, v54
	s_nop 0
	v_fma_f32 v57, -v54, v55, 1.0
	v_fmac_f32_e32 v55, v57, v55
	v_div_scale_f32 v57, vcc, 1.0, v53, 1.0
	v_mul_f32_e32 v58, v57, v55
	v_fma_f32 v59, -v54, v58, v57
	v_fmac_f32_e32 v58, v59, v55
	v_fma_f32 v54, -v54, v58, v57
	v_div_fmas_f32 v54, v54, v55, v58
	v_div_fixup_f32 v53, v54, v53, 1.0
	v_div_scale_f32 v54, s[28:29], v52, v52, 1.0
	v_rcp_f32_e32 v55, v54
	s_nop 0
	v_fma_f32 v57, -v54, v55, 1.0
	v_fmac_f32_e32 v55, v57, v55
	v_div_scale_f32 v57, vcc, 1.0, v52, 1.0
	v_mul_f32_e32 v58, v57, v55
	v_fma_f32 v59, -v54, v58, v57
	v_fmac_f32_e32 v58, v59, v55
	v_fma_f32 v54, -v54, v58, v57
	v_div_fmas_f32 v54, v54, v55, v58
	v_div_fixup_f32 v52, v54, v52, 1.0
	v_cvt_pk_bf16_f32 v52, v52, v53
	ds_write2st64_b32 v162, v56, v52 offset0:208 offset1:212
	v_div_scale_f32 v52, s[28:29], v49, v49, 1.0
	v_rcp_f32_e32 v53, v52
	s_nop 0
	v_fma_f32 v54, -v52, v53, 1.0
	v_fmac_f32_e32 v53, v54, v53
	v_div_scale_f32 v54, vcc, 1.0, v49, 1.0
	v_mul_f32_e32 v55, v54, v53
	v_fma_f32 v56, -v52, v55, v54
	v_fmac_f32_e32 v55, v56, v53
	v_fma_f32 v52, -v52, v55, v54
	v_div_fmas_f32 v52, v52, v53, v55
	v_div_fixup_f32 v49, v52, v49, 1.0
	v_div_scale_f32 v52, s[28:29], v48, v48, 1.0
	v_rcp_f32_e32 v53, v52
	s_nop 0
	v_fma_f32 v54, -v52, v53, 1.0
	v_fmac_f32_e32 v53, v54, v53
	v_div_scale_f32 v54, vcc, 1.0, v48, 1.0
	v_mul_f32_e32 v55, v54, v53
	v_fma_f32 v56, -v52, v55, v54
	v_fmac_f32_e32 v55, v56, v53
	v_fma_f32 v52, -v52, v55, v54
	v_div_fmas_f32 v52, v52, v53, v55
	v_div_fixup_f32 v48, v52, v48, 1.0
	v_cvt_pk_bf16_f32 v52, v48, v49
	v_mul_f32_e32 v48, 0xbfb8aa3b, v50
	v_mul_f32_e32 v49, 0xbfb8aa3b, v51
	v_exp_f32_e32 v48, v48
	v_exp_f32_e32 v49, v49
	s_nop 0
	v_pk_add_f32 v[48:49], v[48:49], 1.0 op_sel_hi:[1,0]
	s_nop 0
	v_div_scale_f32 v50, s[28:29], v49, v49, 1.0
	v_rcp_f32_e32 v51, v50
	s_nop 0
	v_fma_f32 v53, -v50, v51, 1.0
	v_fmac_f32_e32 v51, v53, v51
	v_div_scale_f32 v53, vcc, 1.0, v49, 1.0
	v_mul_f32_e32 v54, v53, v51
	v_fma_f32 v55, -v50, v54, v53
	v_fmac_f32_e32 v54, v55, v51
	v_fma_f32 v50, -v50, v54, v53
	v_div_fmas_f32 v50, v50, v51, v54
	v_div_fixup_f32 v49, v50, v49, 1.0
	v_div_scale_f32 v50, s[28:29], v48, v48, 1.0
	v_rcp_f32_e32 v51, v50
	s_nop 0
	v_fma_f32 v53, -v50, v51, 1.0
	v_fmac_f32_e32 v51, v53, v51
	v_div_scale_f32 v53, vcc, 1.0, v48, 1.0
	v_mul_f32_e32 v54, v53, v51
	v_fma_f32 v55, -v50, v54, v53
	v_fmac_f32_e32 v54, v55, v51
	v_fma_f32 v50, -v50, v54, v53
	v_div_fmas_f32 v50, v50, v51, v54
	v_div_fixup_f32 v48, v50, v48, 1.0
	v_cvt_pk_bf16_f32 v48, v48, v49
	ds_write2st64_b32 v162, v52, v48 offset0:216 offset1:220
	v_div_scale_f32 v48, s[28:29], v45, v45, 1.0
	v_rcp_f32_e32 v49, v48
	s_nop 0
	v_fma_f32 v50, -v48, v49, 1.0
	v_fmac_f32_e32 v49, v50, v49
	v_div_scale_f32 v50, vcc, 1.0, v45, 1.0
	v_mul_f32_e32 v51, v50, v49
	v_fma_f32 v52, -v48, v51, v50
	v_fmac_f32_e32 v51, v52, v49
	v_fma_f32 v48, -v48, v51, v50
	v_div_fmas_f32 v48, v48, v49, v51
	v_div_fixup_f32 v45, v48, v45, 1.0
	v_div_scale_f32 v48, s[28:29], v44, v44, 1.0
	v_rcp_f32_e32 v49, v48
	s_nop 0
	v_fma_f32 v50, -v48, v49, 1.0
	v_fmac_f32_e32 v49, v50, v49
	v_div_scale_f32 v50, vcc, 1.0, v44, 1.0
	v_mul_f32_e32 v51, v50, v49
	v_fma_f32 v52, -v48, v51, v50
	v_fmac_f32_e32 v51, v52, v49
	v_fma_f32 v48, -v48, v51, v50
	v_div_fmas_f32 v48, v48, v49, v51
	v_div_fixup_f32 v44, v48, v44, 1.0
	v_cvt_pk_bf16_f32 v48, v44, v45
	v_mul_f32_e32 v44, 0xbfb8aa3b, v46
	v_mul_f32_e32 v45, 0xbfb8aa3b, v47
	v_exp_f32_e32 v44, v44
	v_exp_f32_e32 v45, v45
	s_nop 0
	v_pk_add_f32 v[44:45], v[44:45], 1.0 op_sel_hi:[1,0]
	s_nop 0
	v_div_scale_f32 v46, s[28:29], v45, v45, 1.0
	v_rcp_f32_e32 v47, v46
	s_nop 0
	v_fma_f32 v49, -v46, v47, 1.0
	v_fmac_f32_e32 v47, v49, v47
	v_div_scale_f32 v49, vcc, 1.0, v45, 1.0
	v_mul_f32_e32 v50, v49, v47
	v_fma_f32 v51, -v46, v50, v49
	v_fmac_f32_e32 v50, v51, v47
	v_fma_f32 v46, -v46, v50, v49
	v_div_fmas_f32 v46, v46, v47, v50
	v_div_fixup_f32 v45, v46, v45, 1.0
	v_div_scale_f32 v46, s[28:29], v44, v44, 1.0
	v_rcp_f32_e32 v47, v46
	s_nop 0
	v_fma_f32 v49, -v46, v47, 1.0
	v_fmac_f32_e32 v47, v49, v47
	v_div_scale_f32 v49, vcc, 1.0, v44, 1.0
	v_mul_f32_e32 v50, v49, v47
	v_fma_f32 v51, -v46, v50, v49
	v_fmac_f32_e32 v50, v51, v47
	v_fma_f32 v46, -v46, v50, v49
	v_div_fmas_f32 v46, v46, v47, v50
	v_div_fixup_f32 v44, v46, v44, 1.0
	v_cvt_pk_bf16_f32 v44, v44, v45
	ds_write2st64_b32 v162, v48, v44 offset0:224 offset1:228
	v_div_scale_f32 v44, s[28:29], v41, v41, 1.0
	v_rcp_f32_e32 v45, v44
	s_nop 0
	v_fma_f32 v46, -v44, v45, 1.0
	v_fmac_f32_e32 v45, v46, v45
	v_div_scale_f32 v46, vcc, 1.0, v41, 1.0
	v_mul_f32_e32 v47, v46, v45
	v_fma_f32 v48, -v44, v47, v46
	v_fmac_f32_e32 v47, v48, v45
	v_fma_f32 v44, -v44, v47, v46
	v_div_fmas_f32 v44, v44, v45, v47
	v_div_fixup_f32 v41, v44, v41, 1.0
	v_div_scale_f32 v44, s[28:29], v40, v40, 1.0
	v_rcp_f32_e32 v45, v44
	s_nop 0
	v_fma_f32 v46, -v44, v45, 1.0
	v_fmac_f32_e32 v45, v46, v45
	v_div_scale_f32 v46, vcc, 1.0, v40, 1.0
	v_mul_f32_e32 v47, v46, v45
	v_fma_f32 v48, -v44, v47, v46
	v_fmac_f32_e32 v47, v48, v45
	v_fma_f32 v44, -v44, v47, v46
	v_div_fmas_f32 v44, v44, v45, v47
	v_div_fixup_f32 v40, v44, v40, 1.0
	v_cvt_pk_bf16_f32 v44, v40, v41
	v_mul_f32_e32 v40, 0xbfb8aa3b, v42
	v_mul_f32_e32 v41, 0xbfb8aa3b, v43
	v_exp_f32_e32 v40, v40
	v_exp_f32_e32 v41, v41
	s_nop 0
	v_pk_add_f32 v[40:41], v[40:41], 1.0 op_sel_hi:[1,0]
	s_nop 0
	v_div_scale_f32 v42, s[28:29], v41, v41, 1.0
	v_rcp_f32_e32 v43, v42
	s_nop 0
	v_fma_f32 v45, -v42, v43, 1.0
	v_fmac_f32_e32 v43, v45, v43
	v_div_scale_f32 v45, vcc, 1.0, v41, 1.0
	v_mul_f32_e32 v46, v45, v43
	v_fma_f32 v47, -v42, v46, v45
	v_fmac_f32_e32 v46, v47, v43
	v_fma_f32 v42, -v42, v46, v45
	v_div_fmas_f32 v42, v42, v43, v46
	v_div_fixup_f32 v41, v42, v41, 1.0
	v_div_scale_f32 v42, s[28:29], v40, v40, 1.0
	v_rcp_f32_e32 v43, v42
	s_nop 0
	v_fma_f32 v45, -v42, v43, 1.0
	v_fmac_f32_e32 v43, v45, v43
	v_div_scale_f32 v45, vcc, 1.0, v40, 1.0
	v_mul_f32_e32 v46, v45, v43
	v_fma_f32 v47, -v42, v46, v45
	v_fmac_f32_e32 v46, v47, v43
	v_fma_f32 v42, -v42, v46, v45
	v_div_fmas_f32 v42, v42, v43, v46
	v_div_fixup_f32 v40, v42, v40, 1.0
	v_cvt_pk_bf16_f32 v40, v40, v41
	ds_write2st64_b32 v162, v44, v40 offset0:232 offset1:236
	v_div_scale_f32 v40, s[28:29], v37, v37, 1.0
	v_rcp_f32_e32 v41, v40
	s_nop 0
	v_fma_f32 v42, -v40, v41, 1.0
	v_fmac_f32_e32 v41, v42, v41
	v_div_scale_f32 v42, vcc, 1.0, v37, 1.0
	v_mul_f32_e32 v43, v42, v41
	v_fma_f32 v44, -v40, v43, v42
	v_fmac_f32_e32 v43, v44, v41
	v_fma_f32 v40, -v40, v43, v42
	v_div_fmas_f32 v40, v40, v41, v43
	v_div_fixup_f32 v37, v40, v37, 1.0
	v_div_scale_f32 v40, s[28:29], v36, v36, 1.0
	v_rcp_f32_e32 v41, v40
	s_nop 0
	v_fma_f32 v42, -v40, v41, 1.0
	v_fmac_f32_e32 v41, v42, v41
	v_div_scale_f32 v42, vcc, 1.0, v36, 1.0
	v_mul_f32_e32 v43, v42, v41
	v_fma_f32 v44, -v40, v43, v42
	v_fmac_f32_e32 v43, v44, v41
	v_fma_f32 v40, -v40, v43, v42
	v_div_fmas_f32 v40, v40, v41, v43
	v_div_fixup_f32 v36, v40, v36, 1.0
	v_cvt_pk_bf16_f32 v40, v36, v37
	v_mul_f32_e32 v36, 0xbfb8aa3b, v38
	v_mul_f32_e32 v37, 0xbfb8aa3b, v39
	v_exp_f32_e32 v36, v36
	v_exp_f32_e32 v37, v37
	s_nop 0
	v_pk_add_f32 v[36:37], v[36:37], 1.0 op_sel_hi:[1,0]
	s_nop 0
	v_div_scale_f32 v38, s[28:29], v37, v37, 1.0
	v_rcp_f32_e32 v39, v38
	s_nop 0
	v_fma_f32 v41, -v38, v39, 1.0
	v_fmac_f32_e32 v39, v41, v39
	v_div_scale_f32 v41, vcc, 1.0, v37, 1.0
	v_mul_f32_e32 v42, v41, v39
	v_fma_f32 v43, -v38, v42, v41
	v_fmac_f32_e32 v42, v43, v39
	v_fma_f32 v38, -v38, v42, v41
	v_div_fmas_f32 v38, v38, v39, v42
	v_div_fixup_f32 v37, v38, v37, 1.0
	v_div_scale_f32 v38, s[28:29], v36, v36, 1.0
	v_rcp_f32_e32 v39, v38
	s_nop 0
	v_fma_f32 v41, -v38, v39, 1.0
	v_fmac_f32_e32 v39, v41, v39
	v_div_scale_f32 v41, vcc, 1.0, v36, 1.0
	v_mul_f32_e32 v42, v41, v39
	v_fma_f32 v43, -v38, v42, v41
	v_fmac_f32_e32 v42, v43, v39
	v_fma_f32 v38, -v38, v42, v41
	v_div_fmas_f32 v38, v38, v39, v42
	v_div_fixup_f32 v36, v38, v36, 1.0
	v_cvt_pk_bf16_f32 v36, v36, v37
	ds_write2st64_b32 v162, v40, v36 offset0:240 offset1:244
	v_div_scale_f32 v36, s[28:29], v33, v33, 1.0
	v_rcp_f32_e32 v37, v36
	s_nop 0
	v_fma_f32 v38, -v36, v37, 1.0
	v_fmac_f32_e32 v37, v38, v37
	v_div_scale_f32 v38, vcc, 1.0, v33, 1.0
	v_mul_f32_e32 v39, v38, v37
	v_fma_f32 v40, -v36, v39, v38
	v_fmac_f32_e32 v39, v40, v37
	v_fma_f32 v36, -v36, v39, v38
	v_div_fmas_f32 v36, v36, v37, v39
	v_div_fixup_f32 v33, v36, v33, 1.0
	v_div_scale_f32 v36, s[28:29], v32, v32, 1.0
	v_rcp_f32_e32 v37, v36
	s_nop 0
	v_fma_f32 v38, -v36, v37, 1.0
	v_fmac_f32_e32 v37, v38, v37
	v_div_scale_f32 v38, vcc, 1.0, v32, 1.0
	v_mul_f32_e32 v39, v38, v37
	v_fma_f32 v40, -v36, v39, v38
	v_fmac_f32_e32 v39, v40, v37
	v_fma_f32 v36, -v36, v39, v38
	v_div_fmas_f32 v36, v36, v37, v39
	v_div_fixup_f32 v32, v36, v32, 1.0
	v_cvt_pk_bf16_f32 v36, v32, v33
	v_mul_f32_e32 v32, 0xbfb8aa3b, v34
	v_mul_f32_e32 v33, 0xbfb8aa3b, v35
	v_exp_f32_e32 v32, v32
	v_exp_f32_e32 v33, v33
	s_nop 0
	v_pk_add_f32 v[32:33], v[32:33], 1.0 op_sel_hi:[1,0]
	s_nop 0
	v_div_scale_f32 v34, s[28:29], v33, v33, 1.0
	v_rcp_f32_e32 v35, v34
	s_nop 0
	v_fma_f32 v37, -v34, v35, 1.0
	v_fmac_f32_e32 v35, v37, v35
	v_div_scale_f32 v37, vcc, 1.0, v33, 1.0
	v_mul_f32_e32 v38, v37, v35
	v_fma_f32 v39, -v34, v38, v37
	v_fmac_f32_e32 v38, v39, v35
	v_fma_f32 v34, -v34, v38, v37
	v_div_fmas_f32 v34, v34, v35, v38
	v_div_fixup_f32 v33, v34, v33, 1.0
	v_div_scale_f32 v34, s[28:29], v32, v32, 1.0
	v_rcp_f32_e32 v35, v34
	s_mov_b64 s[28:29], s[44:45]
	v_fma_f32 v37, -v34, v35, 1.0
	v_fmac_f32_e32 v35, v37, v35
	v_div_scale_f32 v37, vcc, 1.0, v32, 1.0
	v_mul_f32_e32 v38, v37, v35
	v_fma_f32 v39, -v34, v38, v37
	v_fmac_f32_e32 v38, v39, v35
	v_fma_f32 v34, -v34, v38, v37
	v_div_fmas_f32 v34, v34, v35, v38
	v_div_fixup_f32 v32, v34, v32, 1.0
	v_cvt_pk_bf16_f32 v32, v32, v33
	ds_write2st64_b32 v162, v36, v32 offset0:248 offset1:252
	s_cbranch_scc1 .LBB0_93
	s_lshl_b32 s26, s40, 10
	s_addk_i32 s26, 0x400
	s_add_u32 s28, s26, s37
	s_addc_u32 s29, 0, s33
	v_readlane_b32 s0, v239, 18
	s_lshl_b64 s[28:29], s[28:29], 11
	v_readlane_b32 s8, v239, 26
	v_readlane_b32 s9, v239, 27
	s_add_u32 s28, s8, s28
	s_addc_u32 s29, s9, s29
	s_mov_b64 s[92:93], s[38:39]
	v_readlane_b32 s1, v239, 19
	v_readlane_b32 s2, v239, 20
	v_readlane_b32 s3, v239, 21
	v_readlane_b32 s4, v239, 22
	v_readlane_b32 s5, v239, 23
	v_readlane_b32 s6, v239, 24
	v_readlane_b32 s7, v239, 25
	v_readlane_b32 s10, v239, 28
	v_readlane_b32 s11, v239, 29
	v_readlane_b32 s12, v239, 30
	v_readlane_b32 s13, v239, 31
	v_readlane_b32 s14, v239, 32
	v_readlane_b32 s15, v239, 33
.LBB0_93:
	v_mov_b32_e32 v32, v184
	s_movk_i32 s0, 0x70
	v_lshlrev_b32_e32 v34, 4, v32
	v_lshlrev_b32_e32 v36, 3, v32
	v_and_b32_e32 v37, 48, v32
	v_and_b32_e32 v33, 15, v32
	v_and_b32_e32 v35, 0xffffff80, v34
	v_bitop3_b32 v34, v34, s0, v32 bitop3:0x48
	v_bitop3_b32 v166, v36, v37, s0 bitop3:0x6c
	v_lshrrev_b32_e32 v36, 1, v32
	s_mov_b32 s0, 0x1ffffc0
	v_and_or_b32 v33, v36, s0, v33
	v_lshlrev_b32_e32 v32, 7, v32
	s_cmp_lg_u64 s[92:93], 0
	v_mov_b32_e32 v36, 0
	v_lshlrev_b32_e32 v167, 7, v33
	v_and_b32_e32 v168, 0x2780, v32
	s_cselect_b64 s[94:95], -1, 0
	v_xor_b32_e32 v169, 64, v166
	s_mov_b32 s41, 0
	v_add_u32_e32 v170, v35, v34
	v_mov_b32_e32 v37, v36
	v_mov_b32_e32 v38, v36
	v_mov_b32_e32 v39, v36
	v_mov_b32_e32 v32, v36
	v_mov_b32_e32 v33, v36
	v_mov_b32_e32 v34, v36
	v_mov_b32_e32 v35, v36
	v_mov_b32_e32 v40, v36
	v_mov_b32_e32 v41, v36
	v_mov_b32_e32 v42, v36
	v_mov_b32_e32 v43, v36
	v_mov_b32_e32 v44, v36
	v_mov_b32_e32 v45, v36
	v_mov_b32_e32 v46, v36
	v_mov_b32_e32 v47, v36
	v_mov_b32_e32 v48, v36
	v_mov_b32_e32 v49, v36
	v_mov_b32_e32 v50, v36
	v_mov_b32_e32 v51, v36
	v_mov_b32_e32 v52, v36
	v_mov_b32_e32 v53, v36
	v_mov_b32_e32 v54, v36
	v_mov_b32_e32 v55, v36
	v_mov_b32_e32 v56, v36
	v_mov_b32_e32 v57, v36
	v_mov_b32_e32 v58, v36
	v_mov_b32_e32 v59, v36
	v_mov_b32_e32 v60, v36
	v_mov_b32_e32 v61, v36
	v_mov_b32_e32 v62, v36
	v_mov_b32_e32 v63, v36
	v_mov_b32_e32 v64, v36
	v_mov_b32_e32 v65, v36
	v_mov_b32_e32 v66, v36
	v_mov_b32_e32 v67, v36
	v_mov_b32_e32 v68, v36
	v_mov_b32_e32 v69, v36
	v_mov_b32_e32 v70, v36
	v_mov_b32_e32 v71, v36
	v_mov_b32_e32 v72, v36
	v_mov_b32_e32 v73, v36
	v_mov_b32_e32 v74, v36
	v_mov_b32_e32 v75, v36
	v_mov_b32_e32 v76, v36
	v_mov_b32_e32 v77, v36
	v_mov_b32_e32 v78, v36
	v_mov_b32_e32 v79, v36
	v_mov_b32_e32 v80, v36
	v_mov_b32_e32 v81, v36
	v_mov_b32_e32 v82, v36
	v_mov_b32_e32 v83, v36
	v_mov_b32_e32 v84, v36
	v_mov_b32_e32 v85, v36
	v_mov_b32_e32 v86, v36
	v_mov_b32_e32 v87, v36
	v_mov_b32_e32 v88, v36
	v_mov_b32_e32 v89, v36
	v_mov_b32_e32 v90, v36
	v_mov_b32_e32 v91, v36
	v_mov_b32_e32 v92, v36
	v_mov_b32_e32 v93, v36
	v_mov_b32_e32 v94, v36
	v_mov_b32_e32 v95, v36
	s_branch .LBB0_96
.LBB0_95:
	v_add_u32_e32 v160, v168, v166
	v_add_u32_e32 v241, v167, v166
	v_add_u32_e32 v242, v167, v169
	v_add_u32_e32 v243, v168, v169
	ds_read_b128 v[172:175], v160 offset:16384
	ds_read_b128 v[180:183], v241
	ds_read_b128 v[214:217], v160 offset:18432
	ds_read_b128 v[218:221], v160 offset:20480
	ds_read_b128 v[222:225], v160 offset:22528
	ds_read_b128 v[244:247], v241 offset:2048
	ds_read_b128 v[248:251], v241 offset:4096
	ds_read_b128 v[252:255], v241 offset:6144
	s_add_i32 s41, s41, 64
	s_andn2_b64 vcc, exec, s[84:85]
	s_waitcnt lgkmcnt(6)
	v_mfma_f32_16x16x32_bf16 v[92:95], v[172:175], v[180:183], v[92:95]
	s_waitcnt lgkmcnt(5)
	v_mfma_f32_16x16x32_bf16 v[88:91], v[214:217], v[180:183], v[88:91]
	s_waitcnt lgkmcnt(4)
	v_mfma_f32_16x16x32_bf16 v[84:87], v[218:221], v[180:183], v[84:87]
	s_waitcnt lgkmcnt(3)
	v_mfma_f32_16x16x32_bf16 v[80:83], v[222:225], v[180:183], v[80:83]
	ds_read_b128 v[180:183], v242
	s_waitcnt lgkmcnt(3)
	v_mfma_f32_16x16x32_bf16 v[76:79], v[172:175], v[244:247], v[76:79]
	v_mfma_f32_16x16x32_bf16 v[72:75], v[214:217], v[244:247], v[72:75]
	v_mfma_f32_16x16x32_bf16 v[68:71], v[218:221], v[244:247], v[68:71]
	v_mfma_f32_16x16x32_bf16 v[64:67], v[222:225], v[244:247], v[64:67]
	ds_read_b128 v[244:247], v242 offset:2048
	s_waitcnt lgkmcnt(3)
	v_mfma_f32_16x16x32_bf16 v[60:63], v[172:175], v[248:251], v[60:63]
	s_waitcnt lgkmcnt(2)
	v_mfma_f32_16x16x32_bf16 v[44:47], v[172:175], v[252:255], v[44:47]
	ds_read_b128 v[172:175], v243 offset:16384
	v_mfma_f32_16x16x32_bf16 v[56:59], v[214:217], v[248:251], v[56:59]
	v_mfma_f32_16x16x32_bf16 v[40:43], v[214:217], v[252:255], v[40:43]
	ds_read_b128 v[214:217], v243 offset:18432
	v_mfma_f32_16x16x32_bf16 v[52:55], v[218:221], v[248:251], v[52:55]
	v_mfma_f32_16x16x32_bf16 v[32:35], v[218:221], v[252:255], v[32:35]
	ds_read_b128 v[218:221], v243 offset:20480
	v_mfma_f32_16x16x32_bf16 v[48:51], v[222:225], v[248:251], v[48:51]
	v_mfma_f32_16x16x32_bf16 v[36:39], v[222:225], v[252:255], v[36:39]
	ds_read_b128 v[222:225], v243 offset:22528
	ds_read_b128 v[248:251], v242 offset:4096
	ds_read_b128 v[252:255], v242 offset:6144
	s_waitcnt lgkmcnt(5)
	v_mfma_f32_16x16x32_bf16 v[92:95], v[172:175], v[180:183], v[92:95]
	v_mfma_f32_16x16x32_bf16 v[76:79], v[172:175], v[244:247], v[76:79]
	s_waitcnt lgkmcnt(4)
	v_mfma_f32_16x16x32_bf16 v[88:91], v[214:217], v[180:183], v[88:91]
	v_mfma_f32_16x16x32_bf16 v[72:75], v[214:217], v[244:247], v[72:75]
	s_waitcnt lgkmcnt(3)
	v_mfma_f32_16x16x32_bf16 v[84:87], v[218:221], v[180:183], v[84:87]
	v_mfma_f32_16x16x32_bf16 v[68:71], v[218:221], v[244:247], v[68:71]
	s_waitcnt lgkmcnt(2)
	v_mfma_f32_16x16x32_bf16 v[80:83], v[222:225], v[180:183], v[80:83]
	v_mfma_f32_16x16x32_bf16 v[64:67], v[222:225], v[244:247], v[64:67]
	s_waitcnt lgkmcnt(1)
	v_mfma_f32_16x16x32_bf16 v[60:63], v[172:175], v[248:251], v[60:63]
	v_mfma_f32_16x16x32_bf16 v[56:59], v[214:217], v[248:251], v[56:59]
	v_mfma_f32_16x16x32_bf16 v[52:55], v[218:221], v[248:251], v[52:55]
	v_mfma_f32_16x16x32_bf16 v[48:51], v[222:225], v[248:251], v[48:51]
	s_waitcnt lgkmcnt(0)
	s_barrier
	v_mfma_f32_16x16x32_bf16 v[44:47], v[172:175], v[252:255], v[44:47]
	v_mfma_f32_16x16x32_bf16 v[40:43], v[214:217], v[252:255], v[40:43]
	v_mfma_f32_16x16x32_bf16 v[32:35], v[218:221], v[252:255], v[32:35]
	v_mfma_f32_16x16x32_bf16 v[36:39], v[222:225], v[252:255], v[36:39]
	s_cbranch_vccz .LBB0_80
.LBB0_96:
	s_cmpk_gt_u32 s41, 0x1bf
	s_cselect_b64 s[84:85], -1, 0
	s_and_b64 vcc, exec, s[84:85]
	v_lshrrev_b32_e32 v244, 3, v184
	v_and_b32_e32 v245, 7, v184
	s_cbranch_scc1 .Lg3_last_2
	s_mov_b64 s[86:87], s[34:35]
	s_mov_b64 s[88:89], s[50:51]
	s_mov_b32 s90, 10
	s_mov_b32 s91, 0x8000
	s_add_i32 s98, s41, 64
	s_lshl_b32 s98, s98, 1
	s_branch .Lg3_load_2
.Lg3_last_2:
	s_and_b64 vcc, exec, s[94:95]
	s_cbranch_vccz .Lg3_plain_2
	s_mov_b64 s[86:87], s[92:93]
	s_mov_b64 s[88:89], s[28:29]
	s_mov_b32 s90, 11
	s_mov_b32 s91, 0x10000
	s_mov_b32 s98, 0

.Lg3_done_2:
	s_waitcnt lgkmcnt(0)
	s_barrier
	s_branch .LBB0_95
.LBB0_103:
	v_readlane_b32 s2, v236, 22
	v_readlane_b32 s6, v236, 24
	v_readlane_b32 s8, v236, 26
	v_readlane_b32 s10, v236, 28
	v_readlane_b32 s12, v236, 30
	v_readlane_b32 s87, v236, 19
	v_readlane_b32 s1, v236, 21
	v_readlane_b32 s3, v236, 23
	v_readlane_b32 s7, v236, 25
	v_readlane_b32 s9, v236, 27
	v_readlane_b32 s11, v236, 29
	v_readlane_b32 s13, v236, 31
	v_readlane_b32 s14, v236, 32
	v_readlane_b32 s15, v236, 33
	v_readlane_b32 s46, v236, 34
	v_readlane_b32 s44, v236, 35
	s_mov_b32 s45, 0x40000
	s_mov_b32 s47, 0x10000
	s_mov_b32 s48, 0x20000
	s_mov_b32 s49, 0x30000
	s_mov_b32 s50, 0x3a800000
	s_movk_i32 s88, 0x1d80

.LBB0_650:
	s_cmpk_gt_u32 s25, 0x3bf
	s_cselect_b64 s[28:29], -1, 0
	s_cmp_lg_u32 s25, 0
	s_cbranch_scc1 .Ls_nosetup_inproj
	v_add_u32_e32 v176, v183, v181
	v_add_u32_e32 v243, v183, v213
	v_add_u32_e32 v241, v182, v181
	v_add_u32_e32 v242, v182, v213
	v_or_b32_e32 v183, 0x4000, v214
	v_lshrrev_b32_e32 v181, 3, v184
	v_and_b32_e32 v182, 7, v184
	v_lshlrev_b32_e32 v181, 11, v181
	v_lshl_add_u32 v181, v182, 4, v181
	s_waitcnt vmcnt(0)
	ds_write_b128 v214, v[68:71]
	ds_write_b128 v214, v[76:79] offset:4096
	ds_write_b128 v214, v[96:99] offset:16384
	ds_write_b128 v214, v[104:107] offset:20480
	ds_write_b128 v214, v[120:123] offset:32768
	ds_write_b128 v214, v[128:131] offset:36864
	ds_write_b128 v214, v[132:135] offset:40960
	ds_write_b128 v214, v[140:143] offset:45056
	s_movk_i32 s101, 0x80
	s_movk_i32 s100, 0x80
	s_add_u32 s98, s42, s100
	s_addc_u32 s99, s43, 0
	global_load_dwordx4 v[120:123], v181, s[98:99]
	s_add_u32 s98, s42, s100
	s_addc_u32 s99, s43, 0
	s_add_u32 s98, s98, 0x10000
	s_addc_u32 s99, s99, 0
	global_load_dwordx4 v[128:131], v181, s[98:99]
	s_add_u32 s98, s40, s100
	s_addc_u32 s99, s41, 0
	global_load_dwordx4 v[68:71], v181, s[98:99]
	s_add_u32 s98, s40, s100
	s_addc_u32 s99, s41, 0
	s_add_u32 s98, s98, 0x10000
	s_addc_u32 s99, s99, 0
	global_load_dwordx4 v[76:79], v181, s[98:99]
	s_add_u32 s98, s40, s100
	s_addc_u32 s99, s41, 0
	s_add_u32 s98, s98, 0x40000
	s_addc_u32 s99, s99, 0
	global_load_dwordx4 v[96:99], v181, s[98:99]
	s_add_u32 s98, s40, s100
	s_addc_u32 s99, s41, 0
	s_add_u32 s98, s98, 0x50000
	s_addc_u32 s99, s99, 0
	global_load_dwordx4 v[104:107], v181, s[98:99]
	s_add_u32 s98, s42, s100
	s_addc_u32 s99, s43, 0
	s_add_u32 s98, s98, 0x20000
	s_addc_u32 s99, s99, 0
	global_load_dwordx4 v[132:135], v181, s[98:99]
	s_add_u32 s98, s42, s100
	s_addc_u32 s99, s43, 0
	s_add_u32 s98, s98, 0x30000
	s_addc_u32 s99, s99, 0
	global_load_dwordx4 v[140:143], v181, s[98:99]
	s_waitcnt lgkmcnt(0)
	s_barrier
.Ls_nosetup_inproj:
	s_add_i32 s101, s25, 64
	s_and_b32 s101, s101, 0x3ff
	s_lshl_b32 s101, s101, 1
	s_add_i32 s100, s25, 128
	s_and_b32 s100, s100, 0x3ff
	s_lshl_b32 s100, s100, 1
	ds_read_b128 v[216:219], v176 offset:32768
	ds_read_b128 v[232:235], v241
	ds_read_b128 v[220:223], v176 offset:34816
	ds_read_b128 v[224:227], v176 offset:36864
	ds_read_b128 v[228:231], v176 offset:38912
	ds_read_b128 v[244:247], v241 offset:2048
	ds_read_b128 v[248:251], v241 offset:4096
	ds_read_b128 v[252:255], v241 offset:6144
	s_waitcnt lgkmcnt(6)
	v_mfma_f32_16x16x32_bf16 v[172:175], v[216:219], v[232:235], v[172:175]
	s_waitcnt lgkmcnt(5)
	v_mfma_f32_16x16x32_bf16 v[168:171], v[220:223], v[232:235], v[168:171]
	s_waitcnt lgkmcnt(4)
	v_mfma_f32_16x16x32_bf16 v[164:167], v[224:227], v[232:235], v[164:167]
	s_waitcnt lgkmcnt(3)
	v_mfma_f32_16x16x32_bf16 v[160:163], v[228:231], v[232:235], v[160:163]
	ds_read_b128 v[232:235], v242
	s_waitcnt vmcnt(11)
	ds_write_b128 v214, v[84:87] offset:8192
	s_add_u32 s98, s40, s101
	s_addc_u32 s99, s41, 0
	s_add_u32 s98, s98, 0x20000
	s_addc_u32 s99, s99, 0
	global_load_dwordx4 v[84:87], v181, s[98:99]
	s_waitcnt lgkmcnt(4)
	v_mfma_f32_16x16x32_bf16 v[156:159], v[216:219], v[244:247], v[156:159]
	v_mfma_f32_16x16x32_bf16 v[152:155], v[220:223], v[244:247], v[152:155]
	v_mfma_f32_16x16x32_bf16 v[148:151], v[224:227], v[244:247], v[148:151]
	v_mfma_f32_16x16x32_bf16 v[144:147], v[228:231], v[244:247], v[144:147]
	ds_read_b128 v[244:247], v242 offset:2048
	s_waitcnt vmcnt(11)
	ds_write_b128 v214, v[92:95] offset:12288
	s_add_u32 s98, s40, s101
	s_addc_u32 s99, s41, 0
	s_add_u32 s98, s98, 0x30000
	s_addc_u32 s99, s99, 0
	global_load_dwordx4 v[92:95], v181, s[98:99]
	s_waitcnt lgkmcnt(5)
	v_mfma_f32_16x16x32_bf16 v[136:139], v[216:219], v[248:251], v[136:139]
	s_waitcnt lgkmcnt(4)
	v_mfma_f32_16x16x32_bf16 v[88:91], v[216:219], v[252:255], v[88:91]
	ds_read_b128 v[216:219], v243 offset:32768
	v_mfma_f32_16x16x32_bf16 v[124:127], v[220:223], v[248:251], v[124:127]
	v_mfma_f32_16x16x32_bf16 v[80:83], v[220:223], v[252:255], v[80:83]
	ds_read_b128 v[220:223], v243 offset:34816
	v_mfma_f32_16x16x32_bf16 v[112:115], v[224:227], v[248:251], v[112:115]
	v_mfma_f32_16x16x32_bf16 v[72:75], v[224:227], v[252:255], v[72:75]
	ds_read_b128 v[224:227], v243 offset:36864
	v_mfma_f32_16x16x32_bf16 v[100:103], v[228:231], v[248:251], v[100:103]
	v_mfma_f32_16x16x32_bf16 v[64:67], v[228:231], v[252:255], v[64:67]
	ds_read_b128 v[228:231], v243 offset:38912
	ds_read_b128 v[248:251], v242 offset:4096
	ds_read_b128 v[252:255], v242 offset:6144
	s_waitcnt vmcnt(11)
	ds_write_b128 v214, v[108:111] offset:24576
	s_add_u32 s98, s40, s101
	s_addc_u32 s99, s41, 0
	s_add_u32 s98, s98, 0x60000
	s_addc_u32 s99, s99, 0
	global_load_dwordx4 v[108:111], v181, s[98:99]
	s_waitcnt lgkmcnt(6)
	v_mfma_f32_16x16x32_bf16 v[172:175], v[216:219], v[232:235], v[172:175]
	v_mfma_f32_16x16x32_bf16 v[156:159], v[216:219], v[244:247], v[156:159]
	s_waitcnt lgkmcnt(5)
	v_mfma_f32_16x16x32_bf16 v[168:171], v[220:223], v[232:235], v[168:171]
	v_mfma_f32_16x16x32_bf16 v[152:155], v[220:223], v[244:247], v[152:155]
	s_waitcnt vmcnt(11)
	ds_write_b128 v214, v[116:119] offset:28672
	s_add_u32 s98, s40, s101
	s_addc_u32 s99, s41, 0
	s_add_u32 s98, s98, 0x70000
	s_addc_u32 s99, s99, 0
	global_load_dwordx4 v[116:119], v181, s[98:99]
	s_waitcnt lgkmcnt(5)
	v_mfma_f32_16x16x32_bf16 v[164:167], v[224:227], v[232:235], v[164:167]
	v_mfma_f32_16x16x32_bf16 v[148:151], v[224:227], v[244:247], v[148:151]
	s_waitcnt lgkmcnt(4)
	v_mfma_f32_16x16x32_bf16 v[160:163], v[228:231], v[232:235], v[160:163]
	v_mfma_f32_16x16x32_bf16 v[144:147], v[228:231], v[244:247], v[144:147]
	s_waitcnt vmcnt(11)
	ds_write_b128 v183, v[120:123] offset:32768
	s_add_u32 s98, s42, s100
	s_addc_u32 s99, s43, 0
	global_load_dwordx4 v[120:123], v181, s[98:99]
	s_waitcnt lgkmcnt(4)
	v_mfma_f32_16x16x32_bf16 v[136:139], v[216:219], v[248:251], v[136:139]
	v_mfma_f32_16x16x32_bf16 v[124:127], v[220:223], v[248:251], v[124:127]
	v_mfma_f32_16x16x32_bf16 v[112:115], v[224:227], v[248:251], v[112:115]
	v_mfma_f32_16x16x32_bf16 v[100:103], v[228:231], v[248:251], v[100:103]
	s_waitcnt vmcnt(11)
	ds_write_b128 v183, v[128:131] offset:36864
	s_add_u32 s98, s42, s100
	s_addc_u32 s99, s43, 0
	s_add_u32 s98, s98, 0x10000
	s_addc_u32 s99, s99, 0
	global_load_dwordx4 v[128:131], v181, s[98:99]
	s_waitcnt lgkmcnt(0)
	s_barrier
	v_mfma_f32_16x16x32_bf16 v[88:91], v[216:219], v[252:255], v[88:91]
	v_mfma_f32_16x16x32_bf16 v[80:83], v[220:223], v[252:255], v[80:83]
	v_mfma_f32_16x16x32_bf16 v[72:75], v[224:227], v[252:255], v[72:75]
	v_mfma_f32_16x16x32_bf16 v[64:67], v[228:231], v[252:255], v[64:67]
	ds_read_b128 v[216:219], v176 offset:32768
	ds_read_b128 v[232:235], v241 offset:8192
	ds_read_b128 v[220:223], v176 offset:34816
	ds_read_b128 v[224:227], v176 offset:36864
	ds_read_b128 v[228:231], v176 offset:38912
	ds_read_b128 v[244:247], v241 offset:10240
	ds_read_b128 v[248:251], v241 offset:12288
	ds_read_b128 v[252:255], v241 offset:14336
	s_waitcnt lgkmcnt(6)
	v_mfma_f32_16x16x32_bf16 v[60:63], v[216:219], v[232:235], v[60:63]
	s_waitcnt lgkmcnt(5)
	v_mfma_f32_16x16x32_bf16 v[56:59], v[220:223], v[232:235], v[56:59]
	s_waitcnt lgkmcnt(4)
	v_mfma_f32_16x16x32_bf16 v[52:55], v[224:227], v[232:235], v[52:55]
	s_waitcnt lgkmcnt(3)
	v_mfma_f32_16x16x32_bf16 v[48:51], v[228:231], v[232:235], v[48:51]
	ds_read_b128 v[232:235], v242 offset:8192
	s_waitcnt vmcnt(11)
	ds_write_b128 v214, v[68:71]
	s_add_u32 s98, s40, s100
	s_addc_u32 s99, s41, 0
	global_load_dwordx4 v[68:71], v181, s[98:99]
	s_waitcnt lgkmcnt(4)
	v_mfma_f32_16x16x32_bf16 v[44:47], v[216:219], v[244:247], v[44:47]
	v_mfma_f32_16x16x32_bf16 v[40:43], v[220:223], v[244:247], v[40:43]
	v_mfma_f32_16x16x32_bf16 v[36:39], v[224:227], v[244:247], v[36:39]
	v_mfma_f32_16x16x32_bf16 v[32:35], v[228:231], v[244:247], v[32:35]
	ds_read_b128 v[244:247], v242 offset:10240
	s_waitcnt vmcnt(11)
	ds_write_b128 v214, v[76:79] offset:4096
	s_add_u32 s98, s40, s100
	s_addc_u32 s99, s41, 0
	s_add_u32 s98, s98, 0x10000
	s_addc_u32 s99, s99, 0
	global_load_dwordx4 v[76:79], v181, s[98:99]
	s_waitcnt lgkmcnt(5)
	v_mfma_f32_16x16x32_bf16 v[28:31], v[216:219], v[248:251], v[28:31]
	s_waitcnt lgkmcnt(4)
	v_mfma_f32_16x16x32_bf16 v[12:15], v[216:219], v[252:255], v[12:15]
	ds_read_b128 v[216:219], v243 offset:32768
	v_mfma_f32_16x16x32_bf16 v[24:27], v[220:223], v[248:251], v[24:27]
	v_mfma_f32_16x16x32_bf16 v[8:11], v[220:223], v[252:255], v[8:11]
	ds_read_b128 v[220:223], v243 offset:34816
	v_mfma_f32_16x16x32_bf16 v[20:23], v[224:227], v[248:251], v[20:23]
	v_mfma_f32_16x16x32_bf16 v[4:7], v[224:227], v[252:255], v[4:7]
	ds_read_b128 v[224:227], v243 offset:36864
	v_mfma_f32_16x16x32_bf16 v[16:19], v[228:231], v[248:251], v[16:19]
	v_mfma_f32_16x16x32_bf16 v[0:3], v[228:231], v[252:255], v[0:3]
	ds_read_b128 v[228:231], v243 offset:38912
	ds_read_b128 v[248:251], v242 offset:12288
	ds_read_b128 v[252:255], v242 offset:14336
	s_waitcnt vmcnt(11)
	ds_write_b128 v214, v[96:99] offset:16384
	s_add_u32 s98, s40, s100
	s_addc_u32 s99, s41, 0
	s_add_u32 s98, s98, 0x40000
	s_addc_u32 s99, s99, 0
	global_load_dwordx4 v[96:99], v181, s[98:99]
	s_waitcnt lgkmcnt(6)
	v_mfma_f32_16x16x32_bf16 v[60:63], v[216:219], v[232:235], v[60:63]
	v_mfma_f32_16x16x32_bf16 v[44:47], v[216:219], v[244:247], v[44:47]
	s_waitcnt lgkmcnt(5)
	v_mfma_f32_16x16x32_bf16 v[56:59], v[220:223], v[232:235], v[56:59]
	v_mfma_f32_16x16x32_bf16 v[40:43], v[220:223], v[244:247], v[40:43]
	s_waitcnt vmcnt(11)
	ds_write_b128 v214, v[104:107] offset:20480
	s_add_u32 s98, s40, s100
	s_addc_u32 s99, s41, 0
	s_add_u32 s98, s98, 0x50000
	s_addc_u32 s99, s99, 0
	global_load_dwordx4 v[104:107], v181, s[98:99]
	s_waitcnt lgkmcnt(5)
	v_mfma_f32_16x16x32_bf16 v[52:55], v[224:227], v[232:235], v[52:55]
	v_mfma_f32_16x16x32_bf16 v[36:39], v[224:227], v[244:247], v[36:39]
	s_waitcnt lgkmcnt(4)
	v_mfma_f32_16x16x32_bf16 v[48:51], v[228:231], v[232:235], v[48:51]
	v_mfma_f32_16x16x32_bf16 v[32:35], v[228:231], v[244:247], v[32:35]
	s_waitcnt vmcnt(11)
	ds_write_b128 v183, v[132:135] offset:40960
	s_add_u32 s98, s42, s100
	s_addc_u32 s99, s43, 0
	s_add_u32 s98, s98, 0x20000
	s_addc_u32 s99, s99, 0
	global_load_dwordx4 v[132:135], v181, s[98:99]
	s_waitcnt lgkmcnt(4)
	v_mfma_f32_16x16x32_bf16 v[28:31], v[216:219], v[248:251], v[28:31]
	v_mfma_f32_16x16x32_bf16 v[24:27], v[220:223], v[248:251], v[24:27]
	v_mfma_f32_16x16x32_bf16 v[20:23], v[224:227], v[248:251], v[20:23]
	v_mfma_f32_16x16x32_bf16 v[16:19], v[228:231], v[248:251], v[16:19]
	s_waitcnt vmcnt(11)
	ds_write_b128 v183, v[140:143] offset:45056
	s_add_u32 s98, s42, s100
	s_addc_u32 s99, s43, 0
	s_add_u32 s98, s98, 0x30000
	s_addc_u32 s99, s99, 0
	global_load_dwordx4 v[140:143], v181, s[98:99]
	s_waitcnt lgkmcnt(0)
	s_barrier
	v_mfma_f32_16x16x32_bf16 v[12:15], v[216:219], v[252:255], v[12:15]
	v_mfma_f32_16x16x32_bf16 v[8:11], v[220:223], v[252:255], v[8:11]
	v_mfma_f32_16x16x32_bf16 v[4:7], v[224:227], v[252:255], v[4:7]
	v_mfma_f32_16x16x32_bf16 v[0:3], v[228:231], v[252:255], v[0:3]
	v_xor_b32_e32 v176, 0x4000, v176
	v_xor_b32_e32 v243, 0x4000, v243
	v_xor_b32_e32 v183, 0x4000, v183
	s_cmp_lg_u32 s28, 0
	s_cbranch_scc0 .Ls_nodrain_inproj
	s_waitcnt vmcnt(0)
.Ls_nodrain_inproj:
	s_add_i32 s25, s25, 64
	s_andn2_b64 vcc, exec, s[28:29]
	s_cbranch_vccz .LBB0_652
	s_branch .LBB0_650
